# v31: v26 + mid-segment s_setprio 0/1 flip pair replaced by s_nop in all six GEMM loops (priority held across each 32-MFMA segment)
# speedup vs baseline: 1.0144x; 1.0097x over previous
; #define PG8_STAGE(bufoff, gbase, voff) do { _Pragma("unroll") for (int _i = 0; _i < 2; ++_i) \
;         __builtin_amdgcn_global_load_lds((const unsigned*)((const char*)(gbase) + (voff)[_i]), (LAS unsigned*)(lds + (bufoff) + ldsw + _i * 8192), 16, 0, 0); } while (0)
; #define PG8_LDA(dst, b, h) do { _Pragma("unroll") for (int m = 0; m < 4; ++m) _Pragma("unroll") for (int k = 0; k < 2; ++k) dst[m][k] = *(const LAS bf16x8*)(lds + PG8_SA(b, h) + aoff + m * 2048 + k * 1024); } while (0)
; #define PG8_LDB(dst, b, h) do { _Pragma("unroll") for (int n = 0; n < 2; ++n) _Pragma("unroll") for (int k = 0; k < 2; ++k) dst[n][k] = *(const LAS bf16x8*)(lds + PG8_SB(b, h) + boff + n * 2048 + k * 1024); } while (0)
; #define PG8_MMA(ai, bj, At, Bt) do { __builtin_amdgcn_s_setprio(1); _Pragma("unroll") for (int m = 0; m < 4; ++m) _Pragma("unroll") for (int n = 0; n < 2; ++n) _Pragma("unroll") for (int k = 0; k < 2; ++k) \
;         acc[ai][bj][m][n] = __builtin_amdgcn_mfma_f32_16x16x32_bf16(Bt[n][k], At[m][k], acc[ai][bj][m][n], 0, 0, 0); __builtin_amdgcn_s_setprio(0); } while (0)
; #define PG8_WAIT_V(n) asm volatile("s_waitcnt vmcnt(" #n ")" ::: "memory")
; #define PG8_WAIT_L(n) asm volatile("s_waitcnt lgkmcnt(" #n ")" ::: "memory")
; #define PG8_BAR __builtin_amdgcn_s_barrier()
; #define PG8_SCHED __builtin_amdgcn_sched_barrier(0)
; template <class Epi, class Sched, bool ALIGN_EPI, bool SP2>
; __device__ __forceinline__ void gemm_phase(LAS unsigned char* lds, const Gemm g, const Sched& S, const Epi& E) {
;     ...
;             const char* a1 = cA + (size_t)(t + 1) * kstep;
;             const char* a2 = last ? nA : cA + (size_t)(t + 2) * kstep; const char* b2 = last ? nB : cB + (size_t)(t + 2) * kstep;
;             const char* a3 = a2 + kstep; const char* b3 = b2 + kstep;
;             if constexpr (SP2) {
;             PG8_LDB(B0, 0, 0); PG8_LDB(B1, 0, 1); PG8_SCHED; PG8_LDA(At, 0, 0); PG8_STAGE(PG8_SA(1, 1), a1 + hstep, voffA);
;             PG8_WAIT_V(8); PG8_WAIT_L(0); PG8_BAR; PG8_MMA(0, 0, At, B0); PG8_MMA(0, 1, At, B1); PG8_BAR; PG8_SCHED;
;             PG8_LDA(At, 0, 1); PG8_STAGE(PG8_SB(0, 0), b2, voffB); PG8_STAGE(PG8_SB(0, 1), b2 + hstep, voffB); PG8_STAGE(PG8_SA(0, 0), a2, voffA);
;             PG8_WAIT_V(8); PG8_WAIT_L(0); PG8_BAR; PG8_MMA(1, 0, At, B0); PG8_MMA(1, 1, At, B1); PG8_BAR; PG8_SCHED;
.LBB0_216:
	s_add_u32 s8, s6, 0xfffc0080
	s_addc_u32 s9, s7, -1
	s_cmp_eq_u32 s43, 12
	s_cselect_b32 s11, s2, s9
	s_cselect_b32 s10, s3, s8
	s_cselect_b32 s9, s5, s42
	s_cselect_b32 s8, s12, s13
	s_add_i32 m0, s71, 0xc000
	s_nop 0
	global_load_lds_dwordx4 v160, s[6:7]
	s_add_i32 m0, s71, 0xe000
	s_nop 0
	global_load_lds_dwordx4 v162, s[6:7]
	ds_read_b128 v[128:131], v177
	ds_read_b128 v[132:135], v177 offset:1024
	ds_read_b128 v[136:139], v177 offset:2048
	ds_read_b128 v[140:143], v177 offset:3072
	ds_read_b128 v[168:171], v178
	ds_read_b128 v[184:187], v178 offset:1024
	ds_read_b128 v[188:191], v178 offset:2048
	ds_read_b128 v[192:195], v178 offset:3072
	ds_read_b128 v[196:199], v179
	ds_read_b128 v[200:203], v179 offset:1024
	ds_read_b128 v[204:207], v179 offset:2048
	ds_read_b128 v[208:211], v179 offset:3072
	ds_read_b128 v[212:215], v179 offset:4096
	ds_read_b128 v[216:219], v179 offset:5120
	ds_read_b128 v[220:223], v179 offset:6144
	ds_read_b128 v[224:227], v179 offset:7168
	s_waitcnt vmcnt(8)
	s_waitcnt lgkmcnt(0)
	s_barrier
	s_setprio 1
	s_waitcnt lgkmcnt(0)
	v_mfma_f32_16x16x32_bf16 v[124:127], v[128:131], v[196:199], v[124:127]
	v_mfma_f32_16x16x32_bf16 v[120:123], v[136:139], v[196:199], v[120:123]
	v_mfma_f32_16x16x32_bf16 v[116:119], v[128:131], v[204:207], v[116:119]
	v_mfma_f32_16x16x32_bf16 v[112:115], v[136:139], v[204:207], v[112:115]
	v_mfma_f32_16x16x32_bf16 v[108:111], v[128:131], v[212:215], v[108:111]
	v_mfma_f32_16x16x32_bf16 v[104:107], v[136:139], v[212:215], v[104:107]
	v_mfma_f32_16x16x32_bf16 v[100:103], v[128:131], v[220:223], v[100:103]
	v_mfma_f32_16x16x32_bf16 v[96:99], v[136:139], v[220:223], v[96:99]
	v_mfma_f32_16x16x32_bf16 v[124:127], v[132:135], v[200:203], v[124:127]
	v_mfma_f32_16x16x32_bf16 v[120:123], v[140:143], v[200:203], v[120:123]
	v_mfma_f32_16x16x32_bf16 v[116:119], v[132:135], v[208:211], v[116:119]
	v_mfma_f32_16x16x32_bf16 v[112:115], v[140:143], v[208:211], v[112:115]
	v_mfma_f32_16x16x32_bf16 v[108:111], v[132:135], v[216:219], v[108:111]
	v_mfma_f32_16x16x32_bf16 v[104:107], v[140:143], v[216:219], v[104:107]
	v_mfma_f32_16x16x32_bf16 v[100:103], v[132:135], v[224:227], v[100:103]
	v_mfma_f32_16x16x32_bf16 v[96:99], v[140:143], v[224:227], v[96:99]
	s_nop 0
	s_nop 0
	v_mfma_f32_16x16x32_bf16 v[60:63], v[168:171], v[196:199], v[60:63]
	v_mfma_f32_16x16x32_bf16 v[56:59], v[188:191], v[196:199], v[56:59]
	v_mfma_f32_16x16x32_bf16 v[52:55], v[168:171], v[204:207], v[52:55]
	v_mfma_f32_16x16x32_bf16 v[48:51], v[188:191], v[204:207], v[48:51]
	v_mfma_f32_16x16x32_bf16 v[44:47], v[168:171], v[212:215], v[44:47]
	v_mfma_f32_16x16x32_bf16 v[40:43], v[188:191], v[212:215], v[40:43]
	v_mfma_f32_16x16x32_bf16 v[36:39], v[168:171], v[220:223], v[36:39]
	v_mfma_f32_16x16x32_bf16 v[32:35], v[188:191], v[220:223], v[32:35]
	v_mfma_f32_16x16x32_bf16 v[60:63], v[184:187], v[200:203], v[60:63]
	v_mfma_f32_16x16x32_bf16 v[56:59], v[192:195], v[200:203], v[56:59]
	v_mfma_f32_16x16x32_bf16 v[52:55], v[184:187], v[208:211], v[52:55]
	v_mfma_f32_16x16x32_bf16 v[48:51], v[192:195], v[208:211], v[48:51]
	v_mfma_f32_16x16x32_bf16 v[44:47], v[184:187], v[216:219], v[44:47]
	v_mfma_f32_16x16x32_bf16 v[40:43], v[192:195], v[216:219], v[40:43]
	v_mfma_f32_16x16x32_bf16 v[36:39], v[184:187], v[224:227], v[36:39]
	v_mfma_f32_16x16x32_bf16 v[32:35], v[192:195], v[224:227], v[32:35]
	s_setprio 0
	s_barrier
	s_add_i32 s44, s74, s70
	s_mov_b32 m0, s44
	s_nop 0
	global_load_lds_dwordx4 v146, s[8:9]
	s_add_i32 m0, s44, 0x2000
	s_add_u32 s44, s8, 0x40000
	s_addc_u32 s45, s9, 0
	s_add_i32 s50, s75, s70
	global_load_lds_dwordx4 v150, s[8:9]
	s_mov_b32 m0, s50
	s_nop 0
	global_load_lds_dwordx4 v146, s[44:45]
	s_add_i32 m0, s50, 0x2000
	s_nop 0
	global_load_lds_dwordx4 v150, s[44:45]
	s_mov_b32 m0, s71
	s_nop 0
	global_load_lds_dwordx4 v144, s[10:11]
	s_mov_b32 m0, s72
	s_nop 0
	global_load_lds_dwordx4 v148, s[10:11]
	ds_read_b128 v[196:199], v179 offset:16384
	ds_read_b128 v[200:203], v179 offset:17408
	ds_read_b128 v[204:207], v179 offset:18432
	ds_read_b128 v[208:211], v179 offset:19456
	ds_read_b128 v[212:215], v179 offset:20480
	ds_read_b128 v[216:219], v179 offset:21504
	ds_read_b128 v[220:223], v179 offset:22528
	ds_read_b128 v[224:227], v179 offset:23552
	s_waitcnt vmcnt(8)
	s_waitcnt lgkmcnt(0)
	s_barrier
	s_setprio 1
	s_waitcnt lgkmcnt(0)
	v_mfma_f32_16x16x32_bf16 v[92:95], v[128:131], v[196:199], v[92:95]
	v_mfma_f32_16x16x32_bf16 v[88:91], v[136:139], v[196:199], v[88:91]
	v_mfma_f32_16x16x32_bf16 v[84:87], v[128:131], v[204:207], v[84:87]
	v_mfma_f32_16x16x32_bf16 v[80:83], v[136:139], v[204:207], v[80:83]
	v_mfma_f32_16x16x32_bf16 v[76:79], v[128:131], v[212:215], v[76:79]
	v_mfma_f32_16x16x32_bf16 v[72:75], v[136:139], v[212:215], v[72:75]
	v_mfma_f32_16x16x32_bf16 v[68:71], v[128:131], v[220:223], v[68:71]
	v_mfma_f32_16x16x32_bf16 v[64:67], v[136:139], v[220:223], v[64:67]
	v_mfma_f32_16x16x32_bf16 v[92:95], v[132:135], v[200:203], v[92:95]
	v_mfma_f32_16x16x32_bf16 v[88:91], v[140:143], v[200:203], v[88:91]
	v_mfma_f32_16x16x32_bf16 v[84:87], v[132:135], v[208:211], v[84:87]
	v_mfma_f32_16x16x32_bf16 v[80:83], v[140:143], v[208:211], v[80:83]
	v_mfma_f32_16x16x32_bf16 v[76:79], v[132:135], v[216:219], v[76:79]
	v_mfma_f32_16x16x32_bf16 v[72:75], v[140:143], v[216:219], v[72:75]
	v_mfma_f32_16x16x32_bf16 v[68:71], v[132:135], v[224:227], v[68:71]
	v_mfma_f32_16x16x32_bf16 v[64:67], v[140:143], v[224:227], v[64:67]
	s_nop 0
	s_nop 0
	v_mfma_f32_16x16x32_bf16 v[28:31], v[168:171], v[196:199], v[28:31]
	v_mfma_f32_16x16x32_bf16 v[24:27], v[188:191], v[196:199], v[24:27]
	v_mfma_f32_16x16x32_bf16 v[20:23], v[168:171], v[204:207], v[20:23]
	v_mfma_f32_16x16x32_bf16 v[16:19], v[188:191], v[204:207], v[16:19]
	v_mfma_f32_16x16x32_bf16 v[12:15], v[168:171], v[212:215], v[12:15]
	v_mfma_f32_16x16x32_bf16 v[8:11], v[188:191], v[212:215], v[8:11]
	v_mfma_f32_16x16x32_bf16 v[4:7], v[168:171], v[220:223], v[4:7]
	v_mfma_f32_16x16x32_bf16 v[0:3], v[188:191], v[220:223], v[0:3]
	v_mfma_f32_16x16x32_bf16 v[28:31], v[184:187], v[200:203], v[28:31]
	v_mfma_f32_16x16x32_bf16 v[24:27], v[192:195], v[200:203], v[24:27]
	v_mfma_f32_16x16x32_bf16 v[20:23], v[184:187], v[208:211], v[20:23]
	v_mfma_f32_16x16x32_bf16 v[16:19], v[192:195], v[208:211], v[16:19]
	v_mfma_f32_16x16x32_bf16 v[12:15], v[184:187], v[216:219], v[12:15]
	v_mfma_f32_16x16x32_bf16 v[8:11], v[192:195], v[216:219], v[8:11]
	v_mfma_f32_16x16x32_bf16 v[4:7], v[184:187], v[224:227], v[4:7]
	v_mfma_f32_16x16x32_bf16 v[0:3], v[192:195], v[224:227], v[0:3]
	s_setprio 0
	s_barrier
; #define PG8_STAGE(bufoff, gbase, voff) do { _Pragma("unroll") for (int _i = 0; _i < 2; ++_i) \
;         __builtin_amdgcn_global_load_lds((const unsigned*)((const char*)(gbase) + (voff)[_i]), (LAS unsigned*)(lds + (bufoff) + ldsw + _i * 8192), 16, 0, 0); } while (0)
; #define PG8_LDA(dst, b, h) do { _Pragma("unroll") for (int m = 0; m < 4; ++m) _Pragma("unroll") for (int k = 0; k < 2; ++k) dst[m][k] = *(const LAS bf16x8*)(lds + PG8_SA(b, h) + aoff + m * 2048 + k * 1024); } while (0)
; #define PG8_LDB(dst, b, h) do { _Pragma("unroll") for (int n = 0; n < 2; ++n) _Pragma("unroll") for (int k = 0; k < 2; ++k) dst[n][k] = *(const LAS bf16x8*)(lds + PG8_SB(b, h) + boff + n * 2048 + k * 1024); } while (0)
; #define PG8_MMA(ai, bj, At, Bt) do { __builtin_amdgcn_s_setprio(1); _Pragma("unroll") for (int m = 0; m < 4; ++m) _Pragma("unroll") for (int n = 0; n < 2; ++n) _Pragma("unroll") for (int k = 0; k < 2; ++k) \
;         acc[ai][bj][m][n] = __builtin_amdgcn_mfma_f32_16x16x32_bf16(Bt[n][k], At[m][k], acc[ai][bj][m][n], 0, 0, 0); __builtin_amdgcn_s_setprio(0); } while (0)
; #define PG8_WAIT_V(n) asm volatile("s_waitcnt vmcnt(" #n ")" ::: "memory")
; #define PG8_WAIT_L(n) asm volatile("s_waitcnt lgkmcnt(" #n ")" ::: "memory")
; #define PG8_BAR __builtin_amdgcn_s_barrier()
; #define PG8_SCHED __builtin_amdgcn_sched_barrier(0)
; template <class Epi, class Sched, bool ALIGN_EPI, bool SP2>
; __device__ __forceinline__ void gemm_phase(LAS unsigned char* lds, const Gemm g, const Sched& S, const Epi& E) {
;     ...
;             PG8_LDB(B0, 1, 0); PG8_LDB(B1, 1, 1); PG8_SCHED; PG8_LDA(At, 1, 0); PG8_STAGE(PG8_SA(0, 1), a2 + hstep, voffA);
;             PG8_WAIT_V(8); PG8_WAIT_L(0); PG8_BAR; PG8_MMA(0, 0, At, B0); PG8_MMA(0, 1, At, B1); PG8_BAR; PG8_SCHED;
;             PG8_LDA(At, 1, 1); PG8_STAGE(PG8_SB(1, 0), b3, voffB); PG8_STAGE(PG8_SB(1, 1), b3 + hstep, voffB); PG8_STAGE(PG8_SA(1, 0), a3, voffA);
;             PG8_WAIT_V(8); PG8_WAIT_L(0); PG8_BAR; PG8_MMA(1, 0, At, B0); PG8_MMA(1, 1, At, B1); PG8_BAR; PG8_SCHED;
	s_add_i32 s44, 0, 0x18000
	s_add_i32 s45, 0, 0x1c000
	v_add_u32_e32 v140, s44, v174
	v_add_u32_e32 v152, s45, v174
	s_add_u32 s10, s10, 0x40000
	s_addc_u32 s11, s11, 0
	s_mov_b32 m0, s73
	s_nop 0
	global_load_lds_dwordx4 v144, s[10:11]
	s_mov_b32 m0, s82
	s_nop 0
	global_load_lds_dwordx4 v148, s[10:11]
	ds_read_b128 v[128:131], v140
	ds_read_b128 v[132:135], v140 offset:1024
	ds_read_b128 v[136:139], v140 offset:2048
	ds_read_b128 v[140:143], v140 offset:3072
	ds_read_b128 v[168:171], v152
	ds_read_b128 v[184:187], v152 offset:1024
	ds_read_b128 v[188:191], v152 offset:2048
	ds_read_b128 v[192:195], v152 offset:3072
	ds_read_b128 v[196:199], v179 offset:32768
	ds_read_b128 v[200:203], v179 offset:33792
	ds_read_b128 v[204:207], v179 offset:34816
	ds_read_b128 v[208:211], v179 offset:35840
	ds_read_b128 v[212:215], v179 offset:36864
	ds_read_b128 v[216:219], v179 offset:37888
	ds_read_b128 v[220:223], v179 offset:38912
	ds_read_b128 v[224:227], v179 offset:39936
	s_waitcnt vmcnt(8)
	s_waitcnt lgkmcnt(0)
	s_barrier
	s_setprio 1
	s_waitcnt lgkmcnt(0)
	v_mfma_f32_16x16x32_bf16 v[124:127], v[128:131], v[196:199], v[124:127]
	v_mfma_f32_16x16x32_bf16 v[120:123], v[136:139], v[196:199], v[120:123]
	v_mfma_f32_16x16x32_bf16 v[116:119], v[128:131], v[204:207], v[116:119]
	v_mfma_f32_16x16x32_bf16 v[112:115], v[136:139], v[204:207], v[112:115]
	v_mfma_f32_16x16x32_bf16 v[108:111], v[128:131], v[212:215], v[108:111]
	v_mfma_f32_16x16x32_bf16 v[104:107], v[136:139], v[212:215], v[104:107]
	v_mfma_f32_16x16x32_bf16 v[100:103], v[128:131], v[220:223], v[100:103]
	v_mfma_f32_16x16x32_bf16 v[96:99], v[136:139], v[220:223], v[96:99]
	v_mfma_f32_16x16x32_bf16 v[124:127], v[132:135], v[200:203], v[124:127]
	v_mfma_f32_16x16x32_bf16 v[120:123], v[140:143], v[200:203], v[120:123]
	v_mfma_f32_16x16x32_bf16 v[116:119], v[132:135], v[208:211], v[116:119]
	v_mfma_f32_16x16x32_bf16 v[112:115], v[140:143], v[208:211], v[112:115]
	v_mfma_f32_16x16x32_bf16 v[108:111], v[132:135], v[216:219], v[108:111]
	v_mfma_f32_16x16x32_bf16 v[104:107], v[140:143], v[216:219], v[104:107]
	v_mfma_f32_16x16x32_bf16 v[100:103], v[132:135], v[224:227], v[100:103]
	v_mfma_f32_16x16x32_bf16 v[96:99], v[140:143], v[224:227], v[96:99]
	s_nop 0
	s_nop 0
	v_mfma_f32_16x16x32_bf16 v[60:63], v[168:171], v[196:199], v[60:63]
	v_mfma_f32_16x16x32_bf16 v[56:59], v[188:191], v[196:199], v[56:59]
	v_mfma_f32_16x16x32_bf16 v[52:55], v[168:171], v[204:207], v[52:55]
	v_mfma_f32_16x16x32_bf16 v[48:51], v[188:191], v[204:207], v[48:51]
	v_mfma_f32_16x16x32_bf16 v[44:47], v[168:171], v[212:215], v[44:47]
	v_mfma_f32_16x16x32_bf16 v[40:43], v[188:191], v[212:215], v[40:43]
	v_mfma_f32_16x16x32_bf16 v[36:39], v[168:171], v[220:223], v[36:39]
	v_mfma_f32_16x16x32_bf16 v[32:35], v[188:191], v[220:223], v[32:35]
	v_mfma_f32_16x16x32_bf16 v[60:63], v[184:187], v[200:203], v[60:63]
	v_mfma_f32_16x16x32_bf16 v[56:59], v[192:195], v[200:203], v[56:59]
	v_mfma_f32_16x16x32_bf16 v[52:55], v[184:187], v[208:211], v[52:55]
	v_mfma_f32_16x16x32_bf16 v[48:51], v[192:195], v[208:211], v[48:51]
	v_mfma_f32_16x16x32_bf16 v[44:47], v[184:187], v[216:219], v[44:47]
	v_mfma_f32_16x16x32_bf16 v[40:43], v[192:195], v[216:219], v[40:43]
	v_mfma_f32_16x16x32_bf16 v[36:39], v[184:187], v[224:227], v[36:39]
	v_mfma_f32_16x16x32_bf16 v[32:35], v[192:195], v[224:227], v[32:35]
	s_setprio 0
	s_barrier
	s_add_u32 s100, s10, 0xfffc0080
	s_addc_u32 s101, s11, -1
	s_add_u32 s98, s8, 0x80
	s_addc_u32 s99, s9, 0
	s_add_i32 s10, s44, s70
	s_mov_b32 m0, s10
	s_nop 0
	global_load_lds_dwordx4 v146, s[98:99]
	s_add_i32 m0, s10, 0x2000
	s_add_u32 s8, s8, 0x40080
	s_addc_u32 s9, s9, 0
	s_add_i32 s10, s45, s70
	global_load_lds_dwordx4 v150, s[98:99]
	s_mov_b32 m0, s10
	s_nop 0
	global_load_lds_dwordx4 v146, s[8:9]
	s_add_i32 m0, s10, 0x2000
	s_nop 0
	global_load_lds_dwordx4 v150, s[8:9]
	s_mov_b32 m0, s83
	s_nop 0
	global_load_lds_dwordx4 v144, s[100:101]
	s_mov_b32 m0, s84
	s_nop 0
	global_load_lds_dwordx4 v148, s[100:101]
	ds_read_b128 v[196:199], v179 offset:49152
	ds_read_b128 v[200:203], v179 offset:50176
	ds_read_b128 v[204:207], v179 offset:51200
	ds_read_b128 v[208:211], v179 offset:52224
	ds_read_b128 v[212:215], v179 offset:53248
	ds_read_b128 v[216:219], v179 offset:54272
	ds_read_b128 v[220:223], v179 offset:55296
	ds_read_b128 v[224:227], v179 offset:56320
	s_waitcnt vmcnt(8)
	s_waitcnt lgkmcnt(0)
	s_barrier
	s_setprio 1
	s_waitcnt lgkmcnt(0)
	v_mfma_f32_16x16x32_bf16 v[92:95], v[128:131], v[196:199], v[92:95]
	v_mfma_f32_16x16x32_bf16 v[88:91], v[136:139], v[196:199], v[88:91]
	v_mfma_f32_16x16x32_bf16 v[84:87], v[128:131], v[204:207], v[84:87]
	v_mfma_f32_16x16x32_bf16 v[80:83], v[136:139], v[204:207], v[80:83]
	v_mfma_f32_16x16x32_bf16 v[76:79], v[128:131], v[212:215], v[76:79]
	v_mfma_f32_16x16x32_bf16 v[72:75], v[136:139], v[212:215], v[72:75]
	v_mfma_f32_16x16x32_bf16 v[68:71], v[128:131], v[220:223], v[68:71]
	v_mfma_f32_16x16x32_bf16 v[64:67], v[136:139], v[220:223], v[64:67]
	v_mfma_f32_16x16x32_bf16 v[92:95], v[132:135], v[200:203], v[92:95]
	v_mfma_f32_16x16x32_bf16 v[88:91], v[140:143], v[200:203], v[88:91]
	v_mfma_f32_16x16x32_bf16 v[84:87], v[132:135], v[208:211], v[84:87]
	v_mfma_f32_16x16x32_bf16 v[80:83], v[140:143], v[208:211], v[80:83]
	v_mfma_f32_16x16x32_bf16 v[76:79], v[132:135], v[216:219], v[76:79]
	v_mfma_f32_16x16x32_bf16 v[72:75], v[140:143], v[216:219], v[72:75]
	v_mfma_f32_16x16x32_bf16 v[68:71], v[132:135], v[224:227], v[68:71]
	v_mfma_f32_16x16x32_bf16 v[64:67], v[140:143], v[224:227], v[64:67]
	s_nop 0
	s_nop 0
	v_mfma_f32_16x16x32_bf16 v[28:31], v[168:171], v[196:199], v[28:31]
	v_mfma_f32_16x16x32_bf16 v[24:27], v[188:191], v[196:199], v[24:27]
	v_mfma_f32_16x16x32_bf16 v[20:23], v[168:171], v[204:207], v[20:23]
	v_mfma_f32_16x16x32_bf16 v[16:19], v[188:191], v[204:207], v[16:19]
	v_mfma_f32_16x16x32_bf16 v[12:15], v[168:171], v[212:215], v[12:15]
	v_mfma_f32_16x16x32_bf16 v[8:11], v[188:191], v[212:215], v[8:11]
	v_mfma_f32_16x16x32_bf16 v[4:7], v[168:171], v[220:223], v[4:7]
	v_mfma_f32_16x16x32_bf16 v[0:3], v[188:191], v[220:223], v[0:3]
	v_mfma_f32_16x16x32_bf16 v[28:31], v[184:187], v[200:203], v[28:31]
	v_mfma_f32_16x16x32_bf16 v[24:27], v[192:195], v[200:203], v[24:27]
	v_mfma_f32_16x16x32_bf16 v[20:23], v[184:187], v[208:211], v[20:23]
	v_mfma_f32_16x16x32_bf16 v[16:19], v[192:195], v[208:211], v[16:19]
	v_mfma_f32_16x16x32_bf16 v[12:15], v[184:187], v[216:219], v[12:15]
	v_mfma_f32_16x16x32_bf16 v[8:11], v[192:195], v[216:219], v[8:11]
	v_mfma_f32_16x16x32_bf16 v[4:7], v[184:187], v[224:227], v[4:7]
	v_mfma_f32_16x16x32_bf16 v[0:3], v[192:195], v[224:227], v[0:3]
	s_setprio 0
	s_barrier
	s_add_i32 s43, s43, 2
	s_add_u32 s6, s6, 0x100
	s_addc_u32 s7, s7, 0
	s_add_u32 s13, s13, 0x100
	s_addc_u32 s42, s42, 0
	s_cmp_gt_u32 s43, 13
	s_cbranch_scc0 .LBB0_216
	s_and_b64 vcc, exec, s[34:35]
	s_cbranch_vccnz .LBB0_221
	v_lshl_add_u32 v168, s4, 8, v155
	s_cmp_lg_u32 s16, 2
	s_mov_b64 s[4:5], -1
	s_cbranch_scc1 .LBB0_222

; #define PG8_STAGE(bufoff, gbase, voff) do { _Pragma("unroll") for (int _i = 0; _i < 2; ++_i) \
;         __builtin_amdgcn_global_load_lds((const unsigned*)((const char*)(gbase) + (voff)[_i]), (LAS unsigned*)(lds + (bufoff) + ldsw + _i * 8192), 16, 0, 0); } while (0)
; #define PG8_LDA(dst, b, h) do { _Pragma("unroll") for (int m = 0; m < 4; ++m) _Pragma("unroll") for (int k = 0; k < 2; ++k) dst[m][k] = *(const LAS bf16x8*)(lds + PG8_SA(b, h) + aoff + m * 2048 + k * 1024); } while (0)
; #define PG8_LDB(dst, b, h) do { _Pragma("unroll") for (int n = 0; n < 2; ++n) _Pragma("unroll") for (int k = 0; k < 2; ++k) dst[n][k] = *(const LAS bf16x8*)(lds + PG8_SB(b, h) + boff + n * 2048 + k * 1024); } while (0)
; #define PG8_MMA(ai, bj, At, Bt) do { __builtin_amdgcn_s_setprio(1); _Pragma("unroll") for (int m = 0; m < 4; ++m) _Pragma("unroll") for (int n = 0; n < 2; ++n) _Pragma("unroll") for (int k = 0; k < 2; ++k) \
;         acc[ai][bj][m][n] = __builtin_amdgcn_mfma_f32_16x16x32_bf16(Bt[n][k], At[m][k], acc[ai][bj][m][n], 0, 0, 0); __builtin_amdgcn_s_setprio(0); } while (0)
; #define PG8_WAIT_V(n) asm volatile("s_waitcnt vmcnt(" #n ")" ::: "memory")
; #define PG8_WAIT_L(n) asm volatile("s_waitcnt lgkmcnt(" #n ")" ::: "memory")
; #define PG8_BAR __builtin_amdgcn_s_barrier()
; #define PG8_SCHED __builtin_amdgcn_sched_barrier(0)
; template <class Epi, class Sched, bool ALIGN_EPI, bool SP2>
; __device__ __forceinline__ void gemm_phase(LAS unsigned char* lds, const Gemm g, const Sched& S, const Epi& E) {
;     ...
;             const char* a1 = cA + (size_t)(t + 1) * kstep;
;             const char* a2 = last ? nA : cA + (size_t)(t + 2) * kstep; const char* b2 = last ? nB : cB + (size_t)(t + 2) * kstep;
;             const char* a3 = a2 + kstep; const char* b3 = b2 + kstep;
;             if constexpr (SP2) {
;             PG8_LDB(B0, 0, 0); PG8_LDB(B1, 0, 1); PG8_SCHED; PG8_LDA(At, 0, 0); PG8_STAGE(PG8_SA(1, 1), a1 + hstep, voffA);
;             PG8_WAIT_V(8); PG8_WAIT_L(0); PG8_BAR; PG8_MMA(0, 0, At, B0); PG8_MMA(0, 1, At, B1); PG8_BAR; PG8_SCHED;
;             PG8_LDA(At, 0, 1); PG8_STAGE(PG8_SB(0, 0), b2, voffB); PG8_STAGE(PG8_SB(0, 1), b2 + hstep, voffB); PG8_STAGE(PG8_SA(0, 0), a2, voffA);
;             PG8_WAIT_V(8); PG8_WAIT_L(0); PG8_BAR; PG8_MMA(1, 0, At, B0); PG8_MMA(1, 1, At, B1); PG8_BAR; PG8_SCHED;
.LBB0_293:
	ds_read_b128 v[152:155], v149
	ds_read_b128 v[156:159], v149 offset:1024
	ds_read_b128 v[160:163], v149 offset:2048
	ds_read_b128 v[164:167], v149 offset:3072
	ds_read_b128 v[168:171], v150
	ds_read_b128 v[176:179], v150 offset:1024
	ds_read_b128 v[180:183], v150 offset:2048
	ds_read_b128 v[184:187], v150 offset:3072
	s_add_u32 s36, s34, 0xfffc0080
	s_addc_u32 s37, s35, -1
	s_cmp_eq_u32 s62, 12
	s_cselect_b32 s39, s27, s37
	s_cselect_b32 s38, s58, s36
	s_cselect_b32 s37, s25, s61
	s_cselect_b32 s36, s59, s60
	s_add_i32 m0, s23, 0xc000
	ds_read_b128 v[188:191], v151
	ds_read_b128 v[192:195], v151 offset:1024
	ds_read_b128 v[196:199], v151 offset:2048
	ds_read_b128 v[200:203], v151 offset:3072
	ds_read_b128 v[204:207], v151 offset:4096
	ds_read_b128 v[208:211], v151 offset:5120
	ds_read_b128 v[212:215], v151 offset:6144
	ds_read_b128 v[216:219], v151 offset:7168
	global_load_lds_dwordx4 v138, s[34:35]
	s_add_i32 m0, s23, 0xe000
	s_nop 0
	global_load_lds_dwordx4 v140, s[34:35]
	s_waitcnt vmcnt(8)
	s_waitcnt lgkmcnt(0)
	s_barrier
	s_setprio 1
	s_waitcnt lgkmcnt(0)
	v_mfma_f32_16x16x32_bf16 v[124:127], v[152:155], v[188:191], v[124:127]
	v_mfma_f32_16x16x32_bf16 v[120:123], v[160:163], v[188:191], v[120:123]
	v_mfma_f32_16x16x32_bf16 v[116:119], v[152:155], v[196:199], v[116:119]
	v_mfma_f32_16x16x32_bf16 v[112:115], v[160:163], v[196:199], v[112:115]
	v_mfma_f32_16x16x32_bf16 v[100:103], v[152:155], v[204:207], v[100:103]
	v_mfma_f32_16x16x32_bf16 v[96:99], v[160:163], v[204:207], v[96:99]
	v_mfma_f32_16x16x32_bf16 v[84:87], v[152:155], v[212:215], v[84:87]
	v_mfma_f32_16x16x32_bf16 v[80:83], v[160:163], v[212:215], v[80:83]
	v_mfma_f32_16x16x32_bf16 v[124:127], v[156:159], v[192:195], v[124:127]
	v_mfma_f32_16x16x32_bf16 v[120:123], v[164:167], v[192:195], v[120:123]
	v_mfma_f32_16x16x32_bf16 v[116:119], v[156:159], v[200:203], v[116:119]
	v_mfma_f32_16x16x32_bf16 v[112:115], v[164:167], v[200:203], v[112:115]
	v_mfma_f32_16x16x32_bf16 v[100:103], v[156:159], v[208:211], v[100:103]
	v_mfma_f32_16x16x32_bf16 v[96:99], v[164:167], v[208:211], v[96:99]
	v_mfma_f32_16x16x32_bf16 v[84:87], v[156:159], v[216:219], v[84:87]
	v_mfma_f32_16x16x32_bf16 v[80:83], v[164:167], v[216:219], v[80:83]
	s_nop 0
	s_nop 0
	v_mfma_f32_16x16x32_bf16 v[108:111], v[168:171], v[188:191], v[108:111]
	v_mfma_f32_16x16x32_bf16 v[104:107], v[180:183], v[188:191], v[104:107]
	v_mfma_f32_16x16x32_bf16 v[92:95], v[168:171], v[196:199], v[92:95]
	v_mfma_f32_16x16x32_bf16 v[88:91], v[180:183], v[196:199], v[88:91]
	v_mfma_f32_16x16x32_bf16 v[76:79], v[168:171], v[204:207], v[76:79]
	v_mfma_f32_16x16x32_bf16 v[72:75], v[180:183], v[204:207], v[72:75]
	v_mfma_f32_16x16x32_bf16 v[68:71], v[168:171], v[212:215], v[68:71]
	v_mfma_f32_16x16x32_bf16 v[64:67], v[180:183], v[212:215], v[64:67]
	v_mfma_f32_16x16x32_bf16 v[108:111], v[176:179], v[192:195], v[108:111]
	v_mfma_f32_16x16x32_bf16 v[104:107], v[184:187], v[192:195], v[104:107]
	v_mfma_f32_16x16x32_bf16 v[92:95], v[176:179], v[200:203], v[92:95]
	v_mfma_f32_16x16x32_bf16 v[88:91], v[184:187], v[200:203], v[88:91]
	v_mfma_f32_16x16x32_bf16 v[76:79], v[176:179], v[208:211], v[76:79]
	v_mfma_f32_16x16x32_bf16 v[72:75], v[184:187], v[208:211], v[72:75]
	v_mfma_f32_16x16x32_bf16 v[68:71], v[176:179], v[216:219], v[68:71]
	v_mfma_f32_16x16x32_bf16 v[64:67], v[184:187], v[216:219], v[64:67]
	s_setprio 0
	s_barrier
	s_add_i32 s63, s50, s33
	s_mov_b32 m0, s63
	ds_read_b128 v[188:191], v151 offset:16384
	ds_read_b128 v[192:195], v151 offset:17408
	ds_read_b128 v[196:199], v151 offset:18432
	ds_read_b128 v[200:203], v151 offset:19456
	ds_read_b128 v[204:207], v151 offset:20480
	ds_read_b128 v[208:211], v151 offset:21504
	ds_read_b128 v[212:215], v151 offset:22528
	ds_read_b128 v[216:219], v151 offset:23552
	global_load_lds_dwordx4 v130, s[36:37]
	s_add_i32 m0, s63, 0x2000
	s_add_u32 s64, s36, 0x40000
	s_addc_u32 s65, s37, 0
	s_add_i32 s63, s51, s33
	global_load_lds_dwordx4 v134, s[36:37]
	s_mov_b32 m0, s63
	s_nop 0
	global_load_lds_dwordx4 v130, s[64:65]
	s_add_i32 m0, s63, 0x2000
	s_nop 0
	global_load_lds_dwordx4 v134, s[64:65]
	s_mov_b32 m0, s23
	s_nop 0
	global_load_lds_dwordx4 v128, s[38:39]
	s_mov_b32 m0, s42
	s_nop 0
	global_load_lds_dwordx4 v132, s[38:39]
	s_waitcnt vmcnt(8)
	s_waitcnt lgkmcnt(0)
	s_barrier
	s_setprio 1
	s_waitcnt lgkmcnt(0)
	v_mfma_f32_16x16x32_bf16 v[60:63], v[152:155], v[188:191], v[60:63]
	v_mfma_f32_16x16x32_bf16 v[56:59], v[160:163], v[188:191], v[56:59]
	v_mfma_f32_16x16x32_bf16 v[52:55], v[152:155], v[196:199], v[52:55]
	v_mfma_f32_16x16x32_bf16 v[48:51], v[160:163], v[196:199], v[48:51]
	v_mfma_f32_16x16x32_bf16 v[36:39], v[152:155], v[204:207], v[36:39]
	v_mfma_f32_16x16x32_bf16 v[32:35], v[160:163], v[204:207], v[32:35]
	v_mfma_f32_16x16x32_bf16 v[20:23], v[152:155], v[212:215], v[20:23]
	v_mfma_f32_16x16x32_bf16 v[16:19], v[160:163], v[212:215], v[16:19]
	v_mfma_f32_16x16x32_bf16 v[60:63], v[156:159], v[192:195], v[60:63]
	v_mfma_f32_16x16x32_bf16 v[56:59], v[164:167], v[192:195], v[56:59]
	v_mfma_f32_16x16x32_bf16 v[52:55], v[156:159], v[200:203], v[52:55]
	v_mfma_f32_16x16x32_bf16 v[48:51], v[164:167], v[200:203], v[48:51]
	v_mfma_f32_16x16x32_bf16 v[36:39], v[156:159], v[208:211], v[36:39]
	v_mfma_f32_16x16x32_bf16 v[32:35], v[164:167], v[208:211], v[32:35]
	v_mfma_f32_16x16x32_bf16 v[20:23], v[156:159], v[216:219], v[20:23]
	v_mfma_f32_16x16x32_bf16 v[16:19], v[164:167], v[216:219], v[16:19]
	s_nop 0
	s_nop 0
	v_mfma_f32_16x16x32_bf16 v[44:47], v[168:171], v[188:191], v[44:47]
	v_mfma_f32_16x16x32_bf16 v[40:43], v[180:183], v[188:191], v[40:43]
	v_mfma_f32_16x16x32_bf16 v[28:31], v[168:171], v[196:199], v[28:31]
	v_mfma_f32_16x16x32_bf16 v[24:27], v[180:183], v[196:199], v[24:27]
	v_mfma_f32_16x16x32_bf16 v[12:15], v[168:171], v[204:207], v[12:15]
	v_mfma_f32_16x16x32_bf16 v[8:11], v[180:183], v[204:207], v[8:11]
	v_mfma_f32_16x16x32_bf16 v[4:7], v[168:171], v[212:215], v[4:7]
	v_mfma_f32_16x16x32_bf16 v[0:3], v[180:183], v[212:215], v[0:3]
	v_mfma_f32_16x16x32_bf16 v[44:47], v[176:179], v[192:195], v[44:47]
	v_mfma_f32_16x16x32_bf16 v[40:43], v[184:187], v[192:195], v[40:43]
	v_mfma_f32_16x16x32_bf16 v[28:31], v[176:179], v[200:203], v[28:31]
	v_mfma_f32_16x16x32_bf16 v[24:27], v[184:187], v[200:203], v[24:27]
	v_mfma_f32_16x16x32_bf16 v[12:15], v[176:179], v[208:211], v[12:15]
	v_mfma_f32_16x16x32_bf16 v[8:11], v[184:187], v[208:211], v[8:11]
	v_mfma_f32_16x16x32_bf16 v[4:7], v[176:179], v[216:219], v[4:7]
	v_mfma_f32_16x16x32_bf16 v[0:3], v[184:187], v[216:219], v[0:3]
	s_setprio 0
	s_barrier
; #define PG8_STAGE(bufoff, gbase, voff) do { _Pragma("unroll") for (int _i = 0; _i < 2; ++_i) \
;         __builtin_amdgcn_global_load_lds((const unsigned*)((const char*)(gbase) + (voff)[_i]), (LAS unsigned*)(lds + (bufoff) + ldsw + _i * 8192), 16, 0, 0); } while (0)
; #define PG8_LDA(dst, b, h) do { _Pragma("unroll") for (int m = 0; m < 4; ++m) _Pragma("unroll") for (int k = 0; k < 2; ++k) dst[m][k] = *(const LAS bf16x8*)(lds + PG8_SA(b, h) + aoff + m * 2048 + k * 1024); } while (0)
; #define PG8_LDB(dst, b, h) do { _Pragma("unroll") for (int n = 0; n < 2; ++n) _Pragma("unroll") for (int k = 0; k < 2; ++k) dst[n][k] = *(const LAS bf16x8*)(lds + PG8_SB(b, h) + boff + n * 2048 + k * 1024); } while (0)
; #define PG8_MMA(ai, bj, At, Bt) do { __builtin_amdgcn_s_setprio(1); _Pragma("unroll") for (int m = 0; m < 4; ++m) _Pragma("unroll") for (int n = 0; n < 2; ++n) _Pragma("unroll") for (int k = 0; k < 2; ++k) \
;         acc[ai][bj][m][n] = __builtin_amdgcn_mfma_f32_16x16x32_bf16(Bt[n][k], At[m][k], acc[ai][bj][m][n], 0, 0, 0); __builtin_amdgcn_s_setprio(0); } while (0)
; #define PG8_WAIT_V(n) asm volatile("s_waitcnt vmcnt(" #n ")" ::: "memory")
; #define PG8_WAIT_L(n) asm volatile("s_waitcnt lgkmcnt(" #n ")" ::: "memory")
; #define PG8_BAR __builtin_amdgcn_s_barrier()
; #define PG8_SCHED __builtin_amdgcn_sched_barrier(0)
; template <class Epi, class Sched, bool ALIGN_EPI, bool SP2>
; __device__ __forceinline__ void gemm_phase(LAS unsigned char* lds, const Gemm g, const Sched& S, const Epi& E) {
;     ...
;             PG8_LDB(B0, 1, 0); PG8_LDB(B1, 1, 1); PG8_SCHED; PG8_LDA(At, 1, 0); PG8_STAGE(PG8_SA(0, 1), a2 + hstep, voffA);
;             PG8_WAIT_V(8); PG8_WAIT_L(0); PG8_BAR; PG8_MMA(0, 0, At, B0); PG8_MMA(0, 1, At, B1); PG8_BAR; PG8_SCHED;
	s_add_i32 s63, 0, 0x18000
	v_add_u32_e32 v136, s63, v147
	s_add_i32 s64, 0, 0x1c000
	ds_read_b128 v[152:155], v136
	ds_read_b128 v[156:159], v136 offset:1024
	ds_read_b128 v[160:163], v136 offset:2048
	ds_read_b128 v[164:167], v136 offset:3072
	v_add_u32_e32 v136, s64, v147
	ds_read_b128 v[168:171], v136
	ds_read_b128 v[176:179], v136 offset:1024
	ds_read_b128 v[180:183], v136 offset:2048
	ds_read_b128 v[184:187], v136 offset:3072
	s_add_u32 s38, s38, 0x40000
	s_addc_u32 s39, s39, 0
	s_mov_b32 m0, s43
	ds_read_b128 v[188:191], v151 offset:32768
	ds_read_b128 v[192:195], v151 offset:33792
	ds_read_b128 v[196:199], v151 offset:34816
	ds_read_b128 v[200:203], v151 offset:35840
	ds_read_b128 v[204:207], v151 offset:36864
	ds_read_b128 v[208:211], v151 offset:37888
	ds_read_b128 v[212:215], v151 offset:38912
	ds_read_b128 v[216:219], v151 offset:39936
	global_load_lds_dwordx4 v128, s[38:39]
	s_mov_b32 m0, s44
	s_nop 0
	global_load_lds_dwordx4 v132, s[38:39]
	s_waitcnt vmcnt(8)
	s_waitcnt lgkmcnt(0)
	s_barrier
	s_setprio 1
	s_waitcnt lgkmcnt(0)
	v_mfma_f32_16x16x32_bf16 v[124:127], v[152:155], v[188:191], v[124:127]
	v_mfma_f32_16x16x32_bf16 v[120:123], v[160:163], v[188:191], v[120:123]
	v_mfma_f32_16x16x32_bf16 v[116:119], v[152:155], v[196:199], v[116:119]
	v_mfma_f32_16x16x32_bf16 v[112:115], v[160:163], v[196:199], v[112:115]
	v_mfma_f32_16x16x32_bf16 v[100:103], v[152:155], v[204:207], v[100:103]
	v_mfma_f32_16x16x32_bf16 v[96:99], v[160:163], v[204:207], v[96:99]
	v_mfma_f32_16x16x32_bf16 v[84:87], v[152:155], v[212:215], v[84:87]
	v_mfma_f32_16x16x32_bf16 v[80:83], v[160:163], v[212:215], v[80:83]
	v_mfma_f32_16x16x32_bf16 v[124:127], v[156:159], v[192:195], v[124:127]
	v_mfma_f32_16x16x32_bf16 v[120:123], v[164:167], v[192:195], v[120:123]
	v_mfma_f32_16x16x32_bf16 v[116:119], v[156:159], v[200:203], v[116:119]
	v_mfma_f32_16x16x32_bf16 v[112:115], v[164:167], v[200:203], v[112:115]
	v_mfma_f32_16x16x32_bf16 v[100:103], v[156:159], v[208:211], v[100:103]
	v_mfma_f32_16x16x32_bf16 v[96:99], v[164:167], v[208:211], v[96:99]
	v_mfma_f32_16x16x32_bf16 v[84:87], v[156:159], v[216:219], v[84:87]
	v_mfma_f32_16x16x32_bf16 v[80:83], v[164:167], v[216:219], v[80:83]
	s_nop 0
	s_nop 0
	v_mfma_f32_16x16x32_bf16 v[108:111], v[168:171], v[188:191], v[108:111]
	v_mfma_f32_16x16x32_bf16 v[104:107], v[180:183], v[188:191], v[104:107]
	v_mfma_f32_16x16x32_bf16 v[92:95], v[168:171], v[196:199], v[92:95]
	v_mfma_f32_16x16x32_bf16 v[88:91], v[180:183], v[196:199], v[88:91]
	v_mfma_f32_16x16x32_bf16 v[76:79], v[168:171], v[204:207], v[76:79]
	v_mfma_f32_16x16x32_bf16 v[72:75], v[180:183], v[204:207], v[72:75]
	v_mfma_f32_16x16x32_bf16 v[68:71], v[168:171], v[212:215], v[68:71]
	v_mfma_f32_16x16x32_bf16 v[64:67], v[180:183], v[212:215], v[64:67]
	v_mfma_f32_16x16x32_bf16 v[108:111], v[176:179], v[192:195], v[108:111]
	v_mfma_f32_16x16x32_bf16 v[104:107], v[184:187], v[192:195], v[104:107]
	v_mfma_f32_16x16x32_bf16 v[92:95], v[176:179], v[200:203], v[92:95]
	v_mfma_f32_16x16x32_bf16 v[88:91], v[184:187], v[200:203], v[88:91]
	v_mfma_f32_16x16x32_bf16 v[76:79], v[176:179], v[208:211], v[76:79]
	v_mfma_f32_16x16x32_bf16 v[72:75], v[184:187], v[208:211], v[72:75]
	v_mfma_f32_16x16x32_bf16 v[68:71], v[176:179], v[216:219], v[68:71]
	v_mfma_f32_16x16x32_bf16 v[64:67], v[184:187], v[216:219], v[64:67]
	s_setprio 0
	s_barrier
; #define PG8_STAGE(bufoff, gbase, voff) do { _Pragma("unroll") for (int _i = 0; _i < 2; ++_i) \
;         __builtin_amdgcn_global_load_lds((const unsigned*)((const char*)(gbase) + (voff)[_i]), (LAS unsigned*)(lds + (bufoff) + ldsw + _i * 8192), 16, 0, 0); } while (0)
; #define PG8_LDA(dst, b, h) do { _Pragma("unroll") for (int m = 0; m < 4; ++m) _Pragma("unroll") for (int k = 0; k < 2; ++k) dst[m][k] = *(const LAS bf16x8*)(lds + PG8_SA(b, h) + aoff + m * 2048 + k * 1024); } while (0)
; #define PG8_MMA(ai, bj, At, Bt) do { __builtin_amdgcn_s_setprio(1); _Pragma("unroll") for (int m = 0; m < 4; ++m) _Pragma("unroll") for (int n = 0; n < 2; ++n) _Pragma("unroll") for (int k = 0; k < 2; ++k) \
;         acc[ai][bj][m][n] = __builtin_amdgcn_mfma_f32_16x16x32_bf16(Bt[n][k], At[m][k], acc[ai][bj][m][n], 0, 0, 0); __builtin_amdgcn_s_setprio(0); } while (0)
; #define PG8_WAIT_V(n) asm volatile("s_waitcnt vmcnt(" #n ")" ::: "memory")
; #define PG8_WAIT_L(n) asm volatile("s_waitcnt lgkmcnt(" #n ")" ::: "memory")
; #define PG8_BAR __builtin_amdgcn_s_barrier()
; #define PG8_SCHED __builtin_amdgcn_sched_barrier(0)
; template <class Epi, class Sched, bool ALIGN_EPI, bool SP2>
; __device__ __forceinline__ void gemm_phase(LAS unsigned char* lds, const Gemm g, const Sched& S, const Epi& E) {
;     ...
;             PG8_LDA(At, 1, 1); PG8_STAGE(PG8_SB(1, 0), b3, voffB); PG8_STAGE(PG8_SB(1, 1), b3 + hstep, voffB); PG8_STAGE(PG8_SA(1, 0), a3, voffA);
;             PG8_WAIT_V(8); PG8_WAIT_L(0); PG8_BAR; PG8_MMA(1, 0, At, B0); PG8_MMA(1, 1, At, B1); PG8_BAR; PG8_SCHED;
	s_add_u32 s100, s38, 0xfffc0080
	s_addc_u32 s101, s39, -1
	s_add_u32 s98, s36, 0x80
	s_addc_u32 s99, s37, 0
	s_add_i32 s38, s63, s33
	s_mov_b32 m0, s38
	ds_read_b128 v[188:191], v151 offset:49152
	ds_read_b128 v[192:195], v151 offset:50176
	ds_read_b128 v[196:199], v151 offset:51200
	ds_read_b128 v[200:203], v151 offset:52224
	ds_read_b128 v[204:207], v151 offset:53248
	ds_read_b128 v[208:211], v151 offset:54272
	ds_read_b128 v[212:215], v151 offset:55296
	ds_read_b128 v[216:219], v151 offset:56320
	global_load_lds_dwordx4 v130, s[98:99]
	s_add_i32 m0, s38, 0x2000
	s_add_u32 s36, s36, 0x40080
	s_addc_u32 s37, s37, 0
	s_add_i32 s38, s64, s33
	global_load_lds_dwordx4 v134, s[98:99]
	s_mov_b32 m0, s38
	s_nop 0
	global_load_lds_dwordx4 v130, s[36:37]
	s_add_i32 m0, s38, 0x2000
	s_nop 0
	global_load_lds_dwordx4 v134, s[36:37]
	s_mov_b32 m0, s46
	s_nop 0
	global_load_lds_dwordx4 v128, s[100:101]
	s_mov_b32 m0, s47
	s_nop 0
	global_load_lds_dwordx4 v132, s[100:101]
	s_waitcnt vmcnt(8)
	s_waitcnt lgkmcnt(0)
	s_barrier
	s_setprio 1
	s_waitcnt lgkmcnt(0)
	v_mfma_f32_16x16x32_bf16 v[60:63], v[152:155], v[188:191], v[60:63]
	v_mfma_f32_16x16x32_bf16 v[56:59], v[160:163], v[188:191], v[56:59]
	v_mfma_f32_16x16x32_bf16 v[52:55], v[152:155], v[196:199], v[52:55]
	v_mfma_f32_16x16x32_bf16 v[48:51], v[160:163], v[196:199], v[48:51]
	v_mfma_f32_16x16x32_bf16 v[36:39], v[152:155], v[204:207], v[36:39]
	v_mfma_f32_16x16x32_bf16 v[32:35], v[160:163], v[204:207], v[32:35]
	v_mfma_f32_16x16x32_bf16 v[20:23], v[152:155], v[212:215], v[20:23]
	v_mfma_f32_16x16x32_bf16 v[16:19], v[160:163], v[212:215], v[16:19]
	v_mfma_f32_16x16x32_bf16 v[60:63], v[156:159], v[192:195], v[60:63]
	v_mfma_f32_16x16x32_bf16 v[56:59], v[164:167], v[192:195], v[56:59]
	v_mfma_f32_16x16x32_bf16 v[52:55], v[156:159], v[200:203], v[52:55]
	v_mfma_f32_16x16x32_bf16 v[48:51], v[164:167], v[200:203], v[48:51]
	v_mfma_f32_16x16x32_bf16 v[36:39], v[156:159], v[208:211], v[36:39]
	v_mfma_f32_16x16x32_bf16 v[32:35], v[164:167], v[208:211], v[32:35]
	v_mfma_f32_16x16x32_bf16 v[20:23], v[156:159], v[216:219], v[20:23]
	v_mfma_f32_16x16x32_bf16 v[16:19], v[164:167], v[216:219], v[16:19]
	s_nop 0
	s_nop 0
	v_mfma_f32_16x16x32_bf16 v[44:47], v[168:171], v[188:191], v[44:47]
	v_mfma_f32_16x16x32_bf16 v[40:43], v[180:183], v[188:191], v[40:43]
	v_mfma_f32_16x16x32_bf16 v[28:31], v[168:171], v[196:199], v[28:31]
	v_mfma_f32_16x16x32_bf16 v[24:27], v[180:183], v[196:199], v[24:27]
	v_mfma_f32_16x16x32_bf16 v[12:15], v[168:171], v[204:207], v[12:15]
	v_mfma_f32_16x16x32_bf16 v[8:11], v[180:183], v[204:207], v[8:11]
	v_mfma_f32_16x16x32_bf16 v[4:7], v[168:171], v[212:215], v[4:7]
	v_mfma_f32_16x16x32_bf16 v[0:3], v[180:183], v[212:215], v[0:3]
	v_mfma_f32_16x16x32_bf16 v[44:47], v[176:179], v[192:195], v[44:47]
	v_mfma_f32_16x16x32_bf16 v[40:43], v[184:187], v[192:195], v[40:43]
	v_mfma_f32_16x16x32_bf16 v[28:31], v[176:179], v[200:203], v[28:31]
	v_mfma_f32_16x16x32_bf16 v[24:27], v[184:187], v[200:203], v[24:27]
	v_mfma_f32_16x16x32_bf16 v[12:15], v[176:179], v[208:211], v[12:15]
	v_mfma_f32_16x16x32_bf16 v[8:11], v[184:187], v[208:211], v[8:11]
	v_mfma_f32_16x16x32_bf16 v[4:7], v[176:179], v[216:219], v[4:7]
	v_mfma_f32_16x16x32_bf16 v[0:3], v[184:187], v[216:219], v[0:3]
	s_setprio 0
	s_barrier
	s_add_i32 s62, s62, 2
	s_add_u32 s34, s34, 0x100
	s_addc_u32 s35, s35, 0
	s_add_u32 s60, s60, 0x100
	s_addc_u32 s61, s61, 0
	s_cmp_gt_u32 s62, 13
	s_cbranch_scc0 .LBB0_293
	v_readlane_b32 s60, v236, 28
	v_readlane_b32 s64, v236, 32
	v_readlane_b32 s65, v236, 33
	v_readlane_b32 s66, v236, 34
	v_readlane_b32 s67, v236, 35
	v_readlane_b32 s72, v236, 40
	v_readlane_b32 s73, v236, 41
	v_readlane_b32 s74, v236, 42
	v_readlane_b32 s75, v236, 43
	s_mov_b64 s[58:59], s[66:67]
	s_mov_b64 s[64:65], s[72:73]
	s_and_b64 vcc, exec, s[10:11]
	s_mov_b64 s[66:67], s[74:75]
	v_readlane_b32 s61, v236, 29
	v_readlane_b32 s62, v236, 30
	v_readlane_b32 s63, v236, 31
	v_readlane_b32 s68, v236, 36
	v_readlane_b32 s69, v236, 37
	v_readlane_b32 s70, v236, 38
	v_readlane_b32 s71, v236, 39
	s_cbranch_vccz .LBB0_296
	s_barrier

; #define PG8_STAGE(bufoff, gbase, voff) do { _Pragma("unroll") for (int _i = 0; _i < 2; ++_i) \
;         __builtin_amdgcn_global_load_lds((const unsigned*)((const char*)(gbase) + (voff)[_i]), (LAS unsigned*)(lds + (bufoff) + ldsw + _i * 8192), 16, 0, 0); } while (0)
; #define PG8_LDA(dst, b, h) do { _Pragma("unroll") for (int m = 0; m < 4; ++m) _Pragma("unroll") for (int k = 0; k < 2; ++k) dst[m][k] = *(const LAS bf16x8*)(lds + PG8_SA(b, h) + aoff + m * 2048 + k * 1024); } while (0)
; #define PG8_LDB(dst, b, h) do { _Pragma("unroll") for (int n = 0; n < 2; ++n) _Pragma("unroll") for (int k = 0; k < 2; ++k) dst[n][k] = *(const LAS bf16x8*)(lds + PG8_SB(b, h) + boff + n * 2048 + k * 1024); } while (0)
; #define PG8_MMA(ai, bj, At, Bt) do { __builtin_amdgcn_s_setprio(1); _Pragma("unroll") for (int m = 0; m < 4; ++m) _Pragma("unroll") for (int n = 0; n < 2; ++n) _Pragma("unroll") for (int k = 0; k < 2; ++k) \
;         acc[ai][bj][m][n] = __builtin_amdgcn_mfma_f32_16x16x32_bf16(Bt[n][k], At[m][k], acc[ai][bj][m][n], 0, 0, 0); __builtin_amdgcn_s_setprio(0); } while (0)
; #define PG8_WAIT_V(n) asm volatile("s_waitcnt vmcnt(" #n ")" ::: "memory")
; #define PG8_WAIT_L(n) asm volatile("s_waitcnt lgkmcnt(" #n ")" ::: "memory")
; #define PG8_BAR __builtin_amdgcn_s_barrier()
; #define PG8_SCHED __builtin_amdgcn_sched_barrier(0)
; template <class Epi, class Sched, bool ALIGN_EPI, bool SP2>
; __device__ __forceinline__ void gemm_phase(LAS unsigned char* lds, const Gemm g, const Sched& S, const Epi& E) {
;     ...
;             const char* a1 = cA + (size_t)(t + 1) * kstep;
;             const char* a2 = last ? nA : cA + (size_t)(t + 2) * kstep; const char* b2 = last ? nB : cB + (size_t)(t + 2) * kstep;
;             const char* a3 = a2 + kstep; const char* b3 = b2 + kstep;
;             if constexpr (SP2) {
;             PG8_LDB(B0, 0, 0); PG8_LDB(B1, 0, 1); PG8_SCHED; PG8_LDA(At, 0, 0); PG8_STAGE(PG8_SA(1, 1), a1 + hstep, voffA);
;             PG8_WAIT_V(8); PG8_WAIT_L(0); PG8_BAR; PG8_MMA(0, 0, At, B0); PG8_MMA(0, 1, At, B1); PG8_BAR; PG8_SCHED;
;             PG8_LDA(At, 0, 1); PG8_STAGE(PG8_SB(0, 0), b2, voffB); PG8_STAGE(PG8_SB(0, 1), b2 + hstep, voffB); PG8_STAGE(PG8_SA(0, 0), a2, voffA);
;             PG8_WAIT_V(8); PG8_WAIT_L(0); PG8_BAR; PG8_MMA(1, 0, At, B0); PG8_MMA(1, 1, At, B1); PG8_BAR; PG8_SCHED;
.LBB0_468:
	v_add_u32_e32 v140, s62, v187
	v_add_u32_e32 v156, s63, v187
	s_add_u32 s34, s28, 0xfffe0080
	s_addc_u32 s35, s29, -1
	s_cmp_eq_u32 s58, 4
	s_cselect_b32 s37, s21, s35
	s_cselect_b32 s36, s50, s34
	s_cselect_b32 s35, s23, s57
	s_cselect_b32 s34, s51, s56
	s_add_i32 m0, s43, 0xc000
	s_nop 0
	global_load_lds_dwordx4 v176, s[28:29]
	s_add_i32 m0, s43, 0xe000
	s_nop 0
	global_load_lds_dwordx4 v178, s[28:29]
	ds_read_b128 v[128:131], v140
	ds_read_b128 v[132:135], v140 offset:1024
	ds_read_b128 v[136:139], v140 offset:2048
	ds_read_b128 v[140:143], v140 offset:3072
	ds_read_b128 v[144:147], v156
	ds_read_b128 v[148:151], v156 offset:1024
	ds_read_b128 v[152:155], v156 offset:2048
	ds_read_b128 v[156:159], v156 offset:3072
	ds_read_b128 v[160:163], v188
	ds_read_b128 v[190:193], v188 offset:1024
	ds_read_b128 v[194:197], v188 offset:2048
	ds_read_b128 v[198:201], v188 offset:3072
	ds_read_b128 v[202:205], v188 offset:4096
	ds_read_b128 v[206:209], v188 offset:5120
	ds_read_b128 v[210:213], v188 offset:6144
	ds_read_b128 v[214:217], v188 offset:7168
	s_waitcnt vmcnt(8)
	s_waitcnt lgkmcnt(0)
	s_barrier
	s_setprio 1
	s_waitcnt lgkmcnt(0)
	v_mfma_f32_16x16x32_bf16 v[124:127], v[128:131], v[160:163], v[124:127]
	v_mfma_f32_16x16x32_bf16 v[120:123], v[136:139], v[160:163], v[120:123]
	v_mfma_f32_16x16x32_bf16 v[116:119], v[128:131], v[194:197], v[116:119]
	v_mfma_f32_16x16x32_bf16 v[112:115], v[136:139], v[194:197], v[112:115]
	v_mfma_f32_16x16x32_bf16 v[108:111], v[128:131], v[202:205], v[108:111]
	v_mfma_f32_16x16x32_bf16 v[104:107], v[136:139], v[202:205], v[104:107]
	v_mfma_f32_16x16x32_bf16 v[100:103], v[128:131], v[210:213], v[100:103]
	v_mfma_f32_16x16x32_bf16 v[96:99], v[136:139], v[210:213], v[96:99]
	v_mfma_f32_16x16x32_bf16 v[124:127], v[132:135], v[190:193], v[124:127]
	v_mfma_f32_16x16x32_bf16 v[120:123], v[140:143], v[190:193], v[120:123]
	v_mfma_f32_16x16x32_bf16 v[116:119], v[132:135], v[198:201], v[116:119]
	v_mfma_f32_16x16x32_bf16 v[112:115], v[140:143], v[198:201], v[112:115]
	v_mfma_f32_16x16x32_bf16 v[108:111], v[132:135], v[206:209], v[108:111]
	v_mfma_f32_16x16x32_bf16 v[104:107], v[140:143], v[206:209], v[104:107]
	v_mfma_f32_16x16x32_bf16 v[100:103], v[132:135], v[214:217], v[100:103]
	v_mfma_f32_16x16x32_bf16 v[96:99], v[140:143], v[214:217], v[96:99]
	s_nop 0
	s_nop 0
	v_mfma_f32_16x16x32_bf16 v[92:95], v[144:147], v[160:163], v[92:95]
	v_mfma_f32_16x16x32_bf16 v[88:91], v[152:155], v[160:163], v[88:91]
	v_mfma_f32_16x16x32_bf16 v[84:87], v[144:147], v[194:197], v[84:87]
	v_mfma_f32_16x16x32_bf16 v[80:83], v[152:155], v[194:197], v[80:83]
	v_mfma_f32_16x16x32_bf16 v[76:79], v[144:147], v[202:205], v[76:79]
	v_mfma_f32_16x16x32_bf16 v[72:75], v[152:155], v[202:205], v[72:75]
	v_mfma_f32_16x16x32_bf16 v[68:71], v[144:147], v[210:213], v[68:71]
	v_mfma_f32_16x16x32_bf16 v[64:67], v[152:155], v[210:213], v[64:67]
	v_mfma_f32_16x16x32_bf16 v[92:95], v[148:151], v[190:193], v[92:95]
	v_mfma_f32_16x16x32_bf16 v[88:91], v[156:159], v[190:193], v[88:91]
	v_mfma_f32_16x16x32_bf16 v[84:87], v[148:151], v[198:201], v[84:87]
	v_mfma_f32_16x16x32_bf16 v[80:83], v[156:159], v[198:201], v[80:83]
	v_mfma_f32_16x16x32_bf16 v[76:79], v[148:151], v[206:209], v[76:79]
	v_mfma_f32_16x16x32_bf16 v[72:75], v[156:159], v[206:209], v[72:75]
	v_mfma_f32_16x16x32_bf16 v[68:71], v[148:151], v[214:217], v[68:71]
	v_mfma_f32_16x16x32_bf16 v[64:67], v[156:159], v[214:217], v[64:67]
	s_setprio 0
	s_barrier
	s_add_i32 s59, s62, s42
	s_mov_b32 m0, s59
	s_nop 0
	global_load_lds_dwordx4 v166, s[34:35]
	s_add_i32 m0, s59, 0x2000
	s_add_u32 s72, s34, 0x20000
	s_addc_u32 s73, s35, 0
	s_add_i32 s59, s63, s42
	global_load_lds_dwordx4 v170, s[34:35]
	s_mov_b32 m0, s59
	s_nop 0
	global_load_lds_dwordx4 v166, s[72:73]
	s_add_i32 m0, s59, 0x2000
	s_nop 0
	global_load_lds_dwordx4 v170, s[72:73]
	s_mov_b32 m0, s43
	s_nop 0
	global_load_lds_dwordx4 v164, s[36:37]
	s_mov_b32 m0, s44
	s_nop 0
	global_load_lds_dwordx4 v168, s[36:37]
	ds_read_b128 v[160:163], v188 offset:16384
	ds_read_b128 v[190:193], v188 offset:17408
	ds_read_b128 v[194:197], v188 offset:18432
	ds_read_b128 v[198:201], v188 offset:19456
	ds_read_b128 v[202:205], v188 offset:20480
	ds_read_b128 v[206:209], v188 offset:21504
	ds_read_b128 v[210:213], v188 offset:22528
	ds_read_b128 v[214:217], v188 offset:23552
	s_waitcnt vmcnt(8)
	s_waitcnt lgkmcnt(0)
	s_barrier
	s_setprio 1
	s_waitcnt lgkmcnt(0)
	v_mfma_f32_16x16x32_bf16 v[60:63], v[128:131], v[160:163], v[60:63]
	v_mfma_f32_16x16x32_bf16 v[56:59], v[136:139], v[160:163], v[56:59]
	v_mfma_f32_16x16x32_bf16 v[52:55], v[128:131], v[194:197], v[52:55]
	v_mfma_f32_16x16x32_bf16 v[48:51], v[136:139], v[194:197], v[48:51]
	v_mfma_f32_16x16x32_bf16 v[44:47], v[128:131], v[202:205], v[44:47]
	v_mfma_f32_16x16x32_bf16 v[40:43], v[136:139], v[202:205], v[40:43]
	v_mfma_f32_16x16x32_bf16 v[36:39], v[128:131], v[210:213], v[36:39]
	v_mfma_f32_16x16x32_bf16 v[32:35], v[136:139], v[210:213], v[32:35]
	v_mfma_f32_16x16x32_bf16 v[60:63], v[132:135], v[190:193], v[60:63]
	v_mfma_f32_16x16x32_bf16 v[56:59], v[140:143], v[190:193], v[56:59]
	v_mfma_f32_16x16x32_bf16 v[52:55], v[132:135], v[198:201], v[52:55]
	v_mfma_f32_16x16x32_bf16 v[48:51], v[140:143], v[198:201], v[48:51]
	v_mfma_f32_16x16x32_bf16 v[44:47], v[132:135], v[206:209], v[44:47]
	v_mfma_f32_16x16x32_bf16 v[40:43], v[140:143], v[206:209], v[40:43]
	v_mfma_f32_16x16x32_bf16 v[36:39], v[132:135], v[214:217], v[36:39]
	v_mfma_f32_16x16x32_bf16 v[32:35], v[140:143], v[214:217], v[32:35]
	s_nop 0
	s_nop 0
	v_mfma_f32_16x16x32_bf16 v[28:31], v[144:147], v[160:163], v[28:31]
	v_mfma_f32_16x16x32_bf16 v[24:27], v[152:155], v[160:163], v[24:27]
	v_mfma_f32_16x16x32_bf16 v[20:23], v[144:147], v[194:197], v[20:23]
	v_mfma_f32_16x16x32_bf16 v[16:19], v[152:155], v[194:197], v[16:19]
	v_mfma_f32_16x16x32_bf16 v[12:15], v[144:147], v[202:205], v[12:15]
	v_mfma_f32_16x16x32_bf16 v[8:11], v[152:155], v[202:205], v[8:11]
	v_mfma_f32_16x16x32_bf16 v[4:7], v[144:147], v[210:213], v[4:7]
	v_mfma_f32_16x16x32_bf16 v[0:3], v[152:155], v[210:213], v[0:3]
	v_mfma_f32_16x16x32_bf16 v[28:31], v[148:151], v[190:193], v[28:31]
	v_mfma_f32_16x16x32_bf16 v[24:27], v[156:159], v[190:193], v[24:27]
	v_mfma_f32_16x16x32_bf16 v[20:23], v[148:151], v[198:201], v[20:23]
	v_mfma_f32_16x16x32_bf16 v[16:19], v[156:159], v[198:201], v[16:19]
	v_mfma_f32_16x16x32_bf16 v[12:15], v[148:151], v[206:209], v[12:15]
	v_mfma_f32_16x16x32_bf16 v[8:11], v[156:159], v[206:209], v[8:11]
	v_mfma_f32_16x16x32_bf16 v[4:7], v[148:151], v[214:217], v[4:7]
	v_mfma_f32_16x16x32_bf16 v[0:3], v[156:159], v[214:217], v[0:3]
	s_setprio 0
	s_barrier
; #define PG8_STAGE(bufoff, gbase, voff) do { _Pragma("unroll") for (int _i = 0; _i < 2; ++_i) \
;         __builtin_amdgcn_global_load_lds((const unsigned*)((const char*)(gbase) + (voff)[_i]), (LAS unsigned*)(lds + (bufoff) + ldsw + _i * 8192), 16, 0, 0); } while (0)
; #define PG8_LDA(dst, b, h) do { _Pragma("unroll") for (int m = 0; m < 4; ++m) _Pragma("unroll") for (int k = 0; k < 2; ++k) dst[m][k] = *(const LAS bf16x8*)(lds + PG8_SA(b, h) + aoff + m * 2048 + k * 1024); } while (0)
; #define PG8_LDB(dst, b, h) do { _Pragma("unroll") for (int n = 0; n < 2; ++n) _Pragma("unroll") for (int k = 0; k < 2; ++k) dst[n][k] = *(const LAS bf16x8*)(lds + PG8_SB(b, h) + boff + n * 2048 + k * 1024); } while (0)
; #define PG8_MMA(ai, bj, At, Bt) do { __builtin_amdgcn_s_setprio(1); _Pragma("unroll") for (int m = 0; m < 4; ++m) _Pragma("unroll") for (int n = 0; n < 2; ++n) _Pragma("unroll") for (int k = 0; k < 2; ++k) \
;         acc[ai][bj][m][n] = __builtin_amdgcn_mfma_f32_16x16x32_bf16(Bt[n][k], At[m][k], acc[ai][bj][m][n], 0, 0, 0); __builtin_amdgcn_s_setprio(0); } while (0)
; #define PG8_WAIT_V(n) asm volatile("s_waitcnt vmcnt(" #n ")" ::: "memory")
; #define PG8_WAIT_L(n) asm volatile("s_waitcnt lgkmcnt(" #n ")" ::: "memory")
; #define PG8_BAR __builtin_amdgcn_s_barrier()
; #define PG8_SCHED __builtin_amdgcn_sched_barrier(0)
; template <class Epi, class Sched, bool ALIGN_EPI, bool SP2>
; __device__ __forceinline__ void gemm_phase(LAS unsigned char* lds, const Gemm g, const Sched& S, const Epi& E) {
;     ...
;             PG8_LDB(B0, 1, 0); PG8_LDB(B1, 1, 1); PG8_SCHED; PG8_LDA(At, 1, 0); PG8_STAGE(PG8_SA(0, 1), a2 + hstep, voffA);
;             PG8_WAIT_V(8); PG8_WAIT_L(0); PG8_BAR; PG8_MMA(0, 0, At, B0); PG8_MMA(0, 1, At, B1); PG8_BAR; PG8_SCHED;
;             PG8_LDA(At, 1, 1); PG8_STAGE(PG8_SB(1, 0), b3, voffB); PG8_STAGE(PG8_SB(1, 1), b3 + hstep, voffB); PG8_STAGE(PG8_SA(1, 0), a3, voffA);
;             PG8_WAIT_V(8); PG8_WAIT_L(0); PG8_BAR; PG8_MMA(1, 0, At, B0); PG8_MMA(1, 1, At, B1); PG8_BAR; PG8_SCHED;
	s_add_i32 s59, 0, 0x18000
	s_add_i32 s71, 0, 0x1c000
	v_add_u32_e32 v140, s59, v187
	v_add_u32_e32 v156, s71, v187
	s_add_u32 s36, s36, 0x20000
	s_addc_u32 s37, s37, 0
	s_mov_b32 m0, s45
	s_nop 0
	global_load_lds_dwordx4 v164, s[36:37]
	s_mov_b32 m0, s46
	s_nop 0
	global_load_lds_dwordx4 v168, s[36:37]
	ds_read_b128 v[128:131], v140
	ds_read_b128 v[132:135], v140 offset:1024
	ds_read_b128 v[136:139], v140 offset:2048
	ds_read_b128 v[140:143], v140 offset:3072
	ds_read_b128 v[144:147], v156
	ds_read_b128 v[148:151], v156 offset:1024
	ds_read_b128 v[152:155], v156 offset:2048
	ds_read_b128 v[156:159], v156 offset:3072
	ds_read_b128 v[160:163], v188 offset:32768
	ds_read_b128 v[190:193], v188 offset:33792
	ds_read_b128 v[194:197], v188 offset:34816
	ds_read_b128 v[198:201], v188 offset:35840
	ds_read_b128 v[202:205], v188 offset:36864
	ds_read_b128 v[206:209], v188 offset:37888
	ds_read_b128 v[210:213], v188 offset:38912
	ds_read_b128 v[214:217], v188 offset:39936
	s_waitcnt vmcnt(8)
	s_waitcnt lgkmcnt(0)
	s_barrier
	s_setprio 1
	s_waitcnt lgkmcnt(0)
	v_mfma_f32_16x16x32_bf16 v[124:127], v[128:131], v[160:163], v[124:127]
	v_mfma_f32_16x16x32_bf16 v[120:123], v[136:139], v[160:163], v[120:123]
	v_mfma_f32_16x16x32_bf16 v[116:119], v[128:131], v[194:197], v[116:119]
	v_mfma_f32_16x16x32_bf16 v[112:115], v[136:139], v[194:197], v[112:115]
	v_mfma_f32_16x16x32_bf16 v[108:111], v[128:131], v[202:205], v[108:111]
	v_mfma_f32_16x16x32_bf16 v[104:107], v[136:139], v[202:205], v[104:107]
	v_mfma_f32_16x16x32_bf16 v[100:103], v[128:131], v[210:213], v[100:103]
	v_mfma_f32_16x16x32_bf16 v[96:99], v[136:139], v[210:213], v[96:99]
	v_mfma_f32_16x16x32_bf16 v[124:127], v[132:135], v[190:193], v[124:127]
	v_mfma_f32_16x16x32_bf16 v[120:123], v[140:143], v[190:193], v[120:123]
	v_mfma_f32_16x16x32_bf16 v[116:119], v[132:135], v[198:201], v[116:119]
	v_mfma_f32_16x16x32_bf16 v[112:115], v[140:143], v[198:201], v[112:115]
	v_mfma_f32_16x16x32_bf16 v[108:111], v[132:135], v[206:209], v[108:111]
	v_mfma_f32_16x16x32_bf16 v[104:107], v[140:143], v[206:209], v[104:107]
	v_mfma_f32_16x16x32_bf16 v[100:103], v[132:135], v[214:217], v[100:103]
	v_mfma_f32_16x16x32_bf16 v[96:99], v[140:143], v[214:217], v[96:99]
	s_nop 0
	s_nop 0
	v_mfma_f32_16x16x32_bf16 v[92:95], v[144:147], v[160:163], v[92:95]
	v_mfma_f32_16x16x32_bf16 v[88:91], v[152:155], v[160:163], v[88:91]
	v_mfma_f32_16x16x32_bf16 v[84:87], v[144:147], v[194:197], v[84:87]
	v_mfma_f32_16x16x32_bf16 v[80:83], v[152:155], v[194:197], v[80:83]
	v_mfma_f32_16x16x32_bf16 v[76:79], v[144:147], v[202:205], v[76:79]
	v_mfma_f32_16x16x32_bf16 v[72:75], v[152:155], v[202:205], v[72:75]
	v_mfma_f32_16x16x32_bf16 v[68:71], v[144:147], v[210:213], v[68:71]
	v_mfma_f32_16x16x32_bf16 v[64:67], v[152:155], v[210:213], v[64:67]
	v_mfma_f32_16x16x32_bf16 v[92:95], v[148:151], v[190:193], v[92:95]
	v_mfma_f32_16x16x32_bf16 v[88:91], v[156:159], v[190:193], v[88:91]
	v_mfma_f32_16x16x32_bf16 v[84:87], v[148:151], v[198:201], v[84:87]
	v_mfma_f32_16x16x32_bf16 v[80:83], v[156:159], v[198:201], v[80:83]
	v_mfma_f32_16x16x32_bf16 v[76:79], v[148:151], v[206:209], v[76:79]
	v_mfma_f32_16x16x32_bf16 v[72:75], v[156:159], v[206:209], v[72:75]
	v_mfma_f32_16x16x32_bf16 v[68:71], v[148:151], v[214:217], v[68:71]
	v_mfma_f32_16x16x32_bf16 v[64:67], v[156:159], v[214:217], v[64:67]
	s_setprio 0
	s_barrier
	s_add_u32 s100, s36, 0xfffe0080
	s_addc_u32 s101, s37, -1
	s_add_u32 s98, s34, 0x80
	s_addc_u32 s99, s35, 0
	s_add_i32 s36, s59, s42
	s_mov_b32 m0, s36
	s_nop 0
	global_load_lds_dwordx4 v166, s[98:99]
	s_add_i32 m0, s36, 0x2000
	s_add_u32 s34, s34, 0x20080
	s_addc_u32 s35, s35, 0
	s_add_i32 s36, s71, s42
	global_load_lds_dwordx4 v170, s[98:99]
	s_mov_b32 m0, s36
	s_nop 0
	global_load_lds_dwordx4 v166, s[34:35]
	s_add_i32 m0, s36, 0x2000
	s_nop 0
	global_load_lds_dwordx4 v170, s[34:35]
	s_mov_b32 m0, s54
	s_nop 0
	global_load_lds_dwordx4 v164, s[100:101]
	s_mov_b32 m0, s55
	s_nop 0
	global_load_lds_dwordx4 v168, s[100:101]
	ds_read_b128 v[160:163], v188 offset:49152
	ds_read_b128 v[190:193], v188 offset:50176
	ds_read_b128 v[194:197], v188 offset:51200
	ds_read_b128 v[198:201], v188 offset:52224
	ds_read_b128 v[202:205], v188 offset:53248
	ds_read_b128 v[206:209], v188 offset:54272
	ds_read_b128 v[210:213], v188 offset:55296
	ds_read_b128 v[214:217], v188 offset:56320
	s_waitcnt vmcnt(8)
	s_waitcnt lgkmcnt(0)
	s_barrier
	s_setprio 1
	s_waitcnt lgkmcnt(0)
	v_mfma_f32_16x16x32_bf16 v[60:63], v[128:131], v[160:163], v[60:63]
	v_mfma_f32_16x16x32_bf16 v[56:59], v[136:139], v[160:163], v[56:59]
	v_mfma_f32_16x16x32_bf16 v[52:55], v[128:131], v[194:197], v[52:55]
	v_mfma_f32_16x16x32_bf16 v[48:51], v[136:139], v[194:197], v[48:51]
	v_mfma_f32_16x16x32_bf16 v[44:47], v[128:131], v[202:205], v[44:47]
	v_mfma_f32_16x16x32_bf16 v[40:43], v[136:139], v[202:205], v[40:43]
	v_mfma_f32_16x16x32_bf16 v[36:39], v[128:131], v[210:213], v[36:39]
	v_mfma_f32_16x16x32_bf16 v[32:35], v[136:139], v[210:213], v[32:35]
	v_mfma_f32_16x16x32_bf16 v[60:63], v[132:135], v[190:193], v[60:63]
	v_mfma_f32_16x16x32_bf16 v[56:59], v[140:143], v[190:193], v[56:59]
	v_mfma_f32_16x16x32_bf16 v[52:55], v[132:135], v[198:201], v[52:55]
	v_mfma_f32_16x16x32_bf16 v[48:51], v[140:143], v[198:201], v[48:51]
	v_mfma_f32_16x16x32_bf16 v[44:47], v[132:135], v[206:209], v[44:47]
	v_mfma_f32_16x16x32_bf16 v[40:43], v[140:143], v[206:209], v[40:43]
	v_mfma_f32_16x16x32_bf16 v[36:39], v[132:135], v[214:217], v[36:39]
	v_mfma_f32_16x16x32_bf16 v[32:35], v[140:143], v[214:217], v[32:35]
	s_nop 0
	s_nop 0
	v_mfma_f32_16x16x32_bf16 v[28:31], v[144:147], v[160:163], v[28:31]
	v_mfma_f32_16x16x32_bf16 v[24:27], v[152:155], v[160:163], v[24:27]
	v_mfma_f32_16x16x32_bf16 v[20:23], v[144:147], v[194:197], v[20:23]
	v_mfma_f32_16x16x32_bf16 v[16:19], v[152:155], v[194:197], v[16:19]
	v_mfma_f32_16x16x32_bf16 v[12:15], v[144:147], v[202:205], v[12:15]
	v_mfma_f32_16x16x32_bf16 v[8:11], v[152:155], v[202:205], v[8:11]
	v_mfma_f32_16x16x32_bf16 v[4:7], v[144:147], v[210:213], v[4:7]
	v_mfma_f32_16x16x32_bf16 v[0:3], v[152:155], v[210:213], v[0:3]
	v_mfma_f32_16x16x32_bf16 v[28:31], v[148:151], v[190:193], v[28:31]
	v_mfma_f32_16x16x32_bf16 v[24:27], v[156:159], v[190:193], v[24:27]
	v_mfma_f32_16x16x32_bf16 v[20:23], v[148:151], v[198:201], v[20:23]
	v_mfma_f32_16x16x32_bf16 v[16:19], v[156:159], v[198:201], v[16:19]
	v_mfma_f32_16x16x32_bf16 v[12:15], v[148:151], v[206:209], v[12:15]
	v_mfma_f32_16x16x32_bf16 v[8:11], v[156:159], v[206:209], v[8:11]
	v_mfma_f32_16x16x32_bf16 v[4:7], v[148:151], v[214:217], v[4:7]
	v_mfma_f32_16x16x32_bf16 v[0:3], v[156:159], v[214:217], v[0:3]
	s_setprio 0
	s_barrier
	s_add_i32 s58, s58, 2
	s_add_u32 s28, s28, 0x100
	s_addc_u32 s29, s29, 0
	s_add_u32 s56, s56, 0x100
	s_addc_u32 s57, s57, 0
	s_cmp_gt_u32 s58, 5
	s_cbranch_scc0 .LBB0_468
	s_and_b64 vcc, exec, s[18:19]
	s_cbranch_vccz .LBB0_471
	s_barrier

; #define PG8_STAGE(bufoff, gbase, voff) do { _Pragma("unroll") for (int _i = 0; _i < 2; ++_i) \
;         __builtin_amdgcn_global_load_lds((const unsigned*)((const char*)(gbase) + (voff)[_i]), (LAS unsigned*)(lds + (bufoff) + ldsw + _i * 8192), 16, 0, 0); } while (0)
; #define PG8_LDA(dst, b, h) do { _Pragma("unroll") for (int m = 0; m < 4; ++m) _Pragma("unroll") for (int k = 0; k < 2; ++k) dst[m][k] = *(const LAS bf16x8*)(lds + PG8_SA(b, h) + aoff + m * 2048 + k * 1024); } while (0)
; #define PG8_LDB(dst, b, h) do { _Pragma("unroll") for (int n = 0; n < 2; ++n) _Pragma("unroll") for (int k = 0; k < 2; ++k) dst[n][k] = *(const LAS bf16x8*)(lds + PG8_SB(b, h) + boff + n * 2048 + k * 1024); } while (0)
; #define PG8_MMA(ai, bj, At, Bt) do { __builtin_amdgcn_s_setprio(1); _Pragma("unroll") for (int m = 0; m < 4; ++m) _Pragma("unroll") for (int n = 0; n < 2; ++n) _Pragma("unroll") for (int k = 0; k < 2; ++k) \
;         acc[ai][bj][m][n] = __builtin_amdgcn_mfma_f32_16x16x32_bf16(Bt[n][k], At[m][k], acc[ai][bj][m][n], 0, 0, 0); __builtin_amdgcn_s_setprio(0); } while (0)
; #define PG8_WAIT_V(n) asm volatile("s_waitcnt vmcnt(" #n ")" ::: "memory")
; #define PG8_WAIT_L(n) asm volatile("s_waitcnt lgkmcnt(" #n ")" ::: "memory")
; #define PG8_BAR __builtin_amdgcn_s_barrier()
; #define PG8_SCHED __builtin_amdgcn_sched_barrier(0)
; template <class Epi, class Sched, bool ALIGN_EPI, bool SP2>
; __device__ __forceinline__ void gemm_phase(LAS unsigned char* lds, const Gemm g, const Sched& S, const Epi& E) {
;     ...
;             const char* a1 = cA + (size_t)(t + 1) * kstep;
;             const char* a2 = last ? nA : cA + (size_t)(t + 2) * kstep; const char* b2 = last ? nB : cB + (size_t)(t + 2) * kstep;
;             const char* a3 = a2 + kstep; const char* b3 = b2 + kstep;
;             if constexpr (SP2) {
;             PG8_LDB(B0, 0, 0); PG8_LDB(B1, 0, 1); PG8_SCHED; PG8_LDA(At, 0, 0); PG8_STAGE(PG8_SA(1, 1), a1 + hstep, voffA);
;             PG8_WAIT_V(8); PG8_WAIT_L(0); PG8_BAR; PG8_MMA(0, 0, At, B0); PG8_MMA(0, 1, At, B1); PG8_BAR; PG8_SCHED;
;             PG8_LDA(At, 0, 1); PG8_STAGE(PG8_SB(0, 0), b2, voffB); PG8_STAGE(PG8_SB(0, 1), b2 + hstep, voffB); PG8_STAGE(PG8_SA(0, 0), a2, voffA);
;             PG8_WAIT_V(8); PG8_WAIT_L(0); PG8_BAR; PG8_MMA(1, 0, At, B0); PG8_MMA(1, 1, At, B1); PG8_BAR; PG8_SCHED;
.LBB0_553:
	ds_read_b128 v[128:131], v167
	ds_read_b128 v[132:135], v167 offset:1024
	ds_read_b128 v[136:139], v167 offset:2048
	ds_read_b128 v[140:143], v167 offset:3072
	ds_read_b128 v[160:163], v168
	ds_read_b128 v[170:173], v168 offset:1024
	ds_read_b128 v[176:179], v168 offset:2048
	ds_read_b128 v[180:183], v168 offset:3072
	s_add_u32 s36, s34, 0xfffc0080
	s_addc_u32 s37, s35, -1
	s_cmp_eq_u32 s59, 12
	s_cselect_b32 s39, s23, s37
	s_cselect_b32 s38, s51, s36
	s_cselect_b32 s37, s25, s58
	s_cselect_b32 s36, s56, s57
	s_add_i32 m0, s31, 0xc000
	ds_read_b128 v[184:187], v169
	ds_read_b128 v[188:191], v169 offset:1024
	ds_read_b128 v[192:195], v169 offset:2048
	ds_read_b128 v[196:199], v169 offset:3072
	ds_read_b128 v[200:203], v169 offset:4096
	ds_read_b128 v[204:207], v169 offset:5120
	ds_read_b128 v[208:211], v169 offset:6144
	ds_read_b128 v[212:215], v169 offset:7168
	global_load_lds_dwordx4 v152, s[34:35]
	s_add_i32 m0, s31, 0xe000
	s_nop 0
	global_load_lds_dwordx4 v154, s[34:35]
	s_waitcnt vmcnt(8)
	s_waitcnt lgkmcnt(0)
	s_barrier
	s_setprio 1
	s_waitcnt lgkmcnt(0)
	v_mfma_f32_16x16x32_bf16 v[124:127], v[128:131], v[184:187], v[124:127]
	v_mfma_f32_16x16x32_bf16 v[120:123], v[136:139], v[184:187], v[120:123]
	v_mfma_f32_16x16x32_bf16 v[108:111], v[128:131], v[192:195], v[108:111]
	v_mfma_f32_16x16x32_bf16 v[104:107], v[136:139], v[192:195], v[104:107]
	v_mfma_f32_16x16x32_bf16 v[92:95], v[128:131], v[200:203], v[92:95]
	v_mfma_f32_16x16x32_bf16 v[88:91], v[136:139], v[200:203], v[88:91]
	v_mfma_f32_16x16x32_bf16 v[76:79], v[128:131], v[208:211], v[76:79]
	v_mfma_f32_16x16x32_bf16 v[72:75], v[136:139], v[208:211], v[72:75]
	v_mfma_f32_16x16x32_bf16 v[124:127], v[132:135], v[188:191], v[124:127]
	v_mfma_f32_16x16x32_bf16 v[120:123], v[140:143], v[188:191], v[120:123]
	v_mfma_f32_16x16x32_bf16 v[108:111], v[132:135], v[196:199], v[108:111]
	v_mfma_f32_16x16x32_bf16 v[104:107], v[140:143], v[196:199], v[104:107]
	v_mfma_f32_16x16x32_bf16 v[92:95], v[132:135], v[204:207], v[92:95]
	v_mfma_f32_16x16x32_bf16 v[88:91], v[140:143], v[204:207], v[88:91]
	v_mfma_f32_16x16x32_bf16 v[76:79], v[132:135], v[212:215], v[76:79]
	v_mfma_f32_16x16x32_bf16 v[72:75], v[140:143], v[212:215], v[72:75]
	s_nop 0
	s_nop 0
	v_mfma_f32_16x16x32_bf16 v[116:119], v[160:163], v[184:187], v[116:119]
	v_mfma_f32_16x16x32_bf16 v[112:115], v[176:179], v[184:187], v[112:115]
	v_mfma_f32_16x16x32_bf16 v[100:103], v[160:163], v[192:195], v[100:103]
	v_mfma_f32_16x16x32_bf16 v[96:99], v[176:179], v[192:195], v[96:99]
	v_mfma_f32_16x16x32_bf16 v[84:87], v[160:163], v[200:203], v[84:87]
	v_mfma_f32_16x16x32_bf16 v[80:83], v[176:179], v[200:203], v[80:83]
	v_mfma_f32_16x16x32_bf16 v[68:71], v[160:163], v[208:211], v[68:71]
	v_mfma_f32_16x16x32_bf16 v[64:67], v[176:179], v[208:211], v[64:67]
	v_mfma_f32_16x16x32_bf16 v[116:119], v[170:173], v[188:191], v[116:119]
	v_mfma_f32_16x16x32_bf16 v[112:115], v[180:183], v[188:191], v[112:115]
	v_mfma_f32_16x16x32_bf16 v[100:103], v[170:173], v[196:199], v[100:103]
	v_mfma_f32_16x16x32_bf16 v[96:99], v[180:183], v[196:199], v[96:99]
	v_mfma_f32_16x16x32_bf16 v[84:87], v[170:173], v[204:207], v[84:87]
	v_mfma_f32_16x16x32_bf16 v[80:83], v[180:183], v[204:207], v[80:83]
	v_mfma_f32_16x16x32_bf16 v[68:71], v[170:173], v[212:215], v[68:71]
	v_mfma_f32_16x16x32_bf16 v[64:67], v[180:183], v[212:215], v[64:67]
	s_setprio 0
	s_barrier
	s_add_i32 s64, s62, s73
	s_mov_b32 m0, s64
	ds_read_b128 v[184:187], v169 offset:16384
	ds_read_b128 v[188:191], v169 offset:17408
	ds_read_b128 v[192:195], v169 offset:18432
	ds_read_b128 v[196:199], v169 offset:19456
	ds_read_b128 v[200:203], v169 offset:20480
	ds_read_b128 v[204:207], v169 offset:21504
	ds_read_b128 v[208:211], v169 offset:22528
	ds_read_b128 v[212:215], v169 offset:23552
	global_load_lds_dwordx4 v146, s[36:37]
	s_add_i32 m0, s64, 0x2000
	s_add_u32 s64, s36, 0x40000
	s_addc_u32 s65, s37, 0
	s_add_i32 s66, s63, s73
	global_load_lds_dwordx4 v150, s[36:37]
	s_mov_b32 m0, s66
	s_nop 0
	global_load_lds_dwordx4 v146, s[64:65]
	s_add_i32 m0, s66, 0x2000
	s_nop 0
	global_load_lds_dwordx4 v150, s[64:65]
	s_mov_b32 m0, s31
	s_nop 0
	global_load_lds_dwordx4 v144, s[38:39]
	s_mov_b32 m0, s68
	s_nop 0
	global_load_lds_dwordx4 v148, s[38:39]
	s_waitcnt vmcnt(8)
	s_waitcnt lgkmcnt(0)
	s_barrier
	s_setprio 1
	s_waitcnt lgkmcnt(0)
	v_mfma_f32_16x16x32_bf16 v[60:63], v[128:131], v[184:187], v[60:63]
	v_mfma_f32_16x16x32_bf16 v[56:59], v[136:139], v[184:187], v[56:59]
	v_mfma_f32_16x16x32_bf16 v[44:47], v[128:131], v[192:195], v[44:47]
	v_mfma_f32_16x16x32_bf16 v[40:43], v[136:139], v[192:195], v[40:43]
	v_mfma_f32_16x16x32_bf16 v[28:31], v[128:131], v[200:203], v[28:31]
	v_mfma_f32_16x16x32_bf16 v[24:27], v[136:139], v[200:203], v[24:27]
	v_mfma_f32_16x16x32_bf16 v[12:15], v[128:131], v[208:211], v[12:15]
	v_mfma_f32_16x16x32_bf16 v[8:11], v[136:139], v[208:211], v[8:11]
	v_mfma_f32_16x16x32_bf16 v[60:63], v[132:135], v[188:191], v[60:63]
	v_mfma_f32_16x16x32_bf16 v[56:59], v[140:143], v[188:191], v[56:59]
	v_mfma_f32_16x16x32_bf16 v[44:47], v[132:135], v[196:199], v[44:47]
	v_mfma_f32_16x16x32_bf16 v[40:43], v[140:143], v[196:199], v[40:43]
	v_mfma_f32_16x16x32_bf16 v[28:31], v[132:135], v[204:207], v[28:31]
	v_mfma_f32_16x16x32_bf16 v[24:27], v[140:143], v[204:207], v[24:27]
	v_mfma_f32_16x16x32_bf16 v[12:15], v[132:135], v[212:215], v[12:15]
	v_mfma_f32_16x16x32_bf16 v[8:11], v[140:143], v[212:215], v[8:11]
	s_nop 0
	s_nop 0
	v_mfma_f32_16x16x32_bf16 v[52:55], v[160:163], v[184:187], v[52:55]
	v_mfma_f32_16x16x32_bf16 v[48:51], v[176:179], v[184:187], v[48:51]
	v_mfma_f32_16x16x32_bf16 v[36:39], v[160:163], v[192:195], v[36:39]
	v_mfma_f32_16x16x32_bf16 v[32:35], v[176:179], v[192:195], v[32:35]
	v_mfma_f32_16x16x32_bf16 v[20:23], v[160:163], v[200:203], v[20:23]
	v_mfma_f32_16x16x32_bf16 v[16:19], v[176:179], v[200:203], v[16:19]
	v_mfma_f32_16x16x32_bf16 v[4:7], v[160:163], v[208:211], v[4:7]
	v_mfma_f32_16x16x32_bf16 v[0:3], v[176:179], v[208:211], v[0:3]
	v_mfma_f32_16x16x32_bf16 v[52:55], v[170:173], v[188:191], v[52:55]
	v_mfma_f32_16x16x32_bf16 v[48:51], v[180:183], v[188:191], v[48:51]
	v_mfma_f32_16x16x32_bf16 v[36:39], v[170:173], v[196:199], v[36:39]
	v_mfma_f32_16x16x32_bf16 v[32:35], v[180:183], v[196:199], v[32:35]
	v_mfma_f32_16x16x32_bf16 v[20:23], v[170:173], v[204:207], v[20:23]
	v_mfma_f32_16x16x32_bf16 v[16:19], v[180:183], v[204:207], v[16:19]
	v_mfma_f32_16x16x32_bf16 v[4:7], v[170:173], v[212:215], v[4:7]
	v_mfma_f32_16x16x32_bf16 v[0:3], v[180:183], v[212:215], v[0:3]
	s_setprio 0
	s_barrier
; #define PG8_STAGE(bufoff, gbase, voff) do { _Pragma("unroll") for (int _i = 0; _i < 2; ++_i) \
;         __builtin_amdgcn_global_load_lds((const unsigned*)((const char*)(gbase) + (voff)[_i]), (LAS unsigned*)(lds + (bufoff) + ldsw + _i * 8192), 16, 0, 0); } while (0)
; #define PG8_LDA(dst, b, h) do { _Pragma("unroll") for (int m = 0; m < 4; ++m) _Pragma("unroll") for (int k = 0; k < 2; ++k) dst[m][k] = *(const LAS bf16x8*)(lds + PG8_SA(b, h) + aoff + m * 2048 + k * 1024); } while (0)
; #define PG8_LDB(dst, b, h) do { _Pragma("unroll") for (int n = 0; n < 2; ++n) _Pragma("unroll") for (int k = 0; k < 2; ++k) dst[n][k] = *(const LAS bf16x8*)(lds + PG8_SB(b, h) + boff + n * 2048 + k * 1024); } while (0)
; #define PG8_MMA(ai, bj, At, Bt) do { __builtin_amdgcn_s_setprio(1); _Pragma("unroll") for (int m = 0; m < 4; ++m) _Pragma("unroll") for (int n = 0; n < 2; ++n) _Pragma("unroll") for (int k = 0; k < 2; ++k) \
;         acc[ai][bj][m][n] = __builtin_amdgcn_mfma_f32_16x16x32_bf16(Bt[n][k], At[m][k], acc[ai][bj][m][n], 0, 0, 0); __builtin_amdgcn_s_setprio(0); } while (0)
; #define PG8_WAIT_V(n) asm volatile("s_waitcnt vmcnt(" #n ")" ::: "memory")
; #define PG8_WAIT_L(n) asm volatile("s_waitcnt lgkmcnt(" #n ")" ::: "memory")
; #define PG8_BAR __builtin_amdgcn_s_barrier()
; #define PG8_SCHED __builtin_amdgcn_sched_barrier(0)
; template <class Epi, class Sched, bool ALIGN_EPI, bool SP2>
; __device__ __forceinline__ void gemm_phase(LAS unsigned char* lds, const Gemm g, const Sched& S, const Epi& E) {
;     ...
;             PG8_LDB(B0, 1, 0); PG8_LDB(B1, 1, 1); PG8_SCHED; PG8_LDA(At, 1, 0); PG8_STAGE(PG8_SA(0, 1), a2 + hstep, voffA);
;             PG8_WAIT_V(8); PG8_WAIT_L(0); PG8_BAR; PG8_MMA(0, 0, At, B0); PG8_MMA(0, 1, At, B1); PG8_BAR; PG8_SCHED;
;             PG8_LDA(At, 1, 1); PG8_STAGE(PG8_SB(1, 0), b3, voffB); PG8_STAGE(PG8_SB(1, 1), b3 + hstep, voffB); PG8_STAGE(PG8_SA(1, 0), a3, voffA);
;             PG8_WAIT_V(8); PG8_WAIT_L(0); PG8_BAR; PG8_MMA(1, 0, At, B0); PG8_MMA(1, 1, At, B1); PG8_BAR; PG8_SCHED;
;     ...
;         }
;         if constexpr (ALIGN_EPI) { if (wr == 0) PG8_BAR; }
	s_add_i32 s64, 0, 0x18000
	s_add_i32 s65, 0, 0x1c000
	v_add_u32_e32 v140, s64, v165
	v_add_u32_e32 v174, s65, v165
	ds_read_b128 v[128:131], v140
	ds_read_b128 v[132:135], v140 offset:1024
	ds_read_b128 v[136:139], v140 offset:2048
	ds_read_b128 v[140:143], v140 offset:3072
	ds_read_b128 v[160:163], v174
	ds_read_b128 v[170:173], v174 offset:1024
	ds_read_b128 v[176:179], v174 offset:2048
	ds_read_b128 v[180:183], v174 offset:3072
	s_add_u32 s38, s38, 0x40000
	s_addc_u32 s39, s39, 0
	s_mov_b32 m0, s69
	ds_read_b128 v[184:187], v169 offset:32768
	ds_read_b128 v[188:191], v169 offset:33792
	ds_read_b128 v[192:195], v169 offset:34816
	ds_read_b128 v[196:199], v169 offset:35840
	ds_read_b128 v[200:203], v169 offset:36864
	ds_read_b128 v[204:207], v169 offset:37888
	ds_read_b128 v[208:211], v169 offset:38912
	ds_read_b128 v[212:215], v169 offset:39936
	global_load_lds_dwordx4 v144, s[38:39]
	s_mov_b32 m0, s70
	s_nop 0
	global_load_lds_dwordx4 v148, s[38:39]
	s_waitcnt vmcnt(8)
	s_waitcnt lgkmcnt(0)
	s_barrier
	s_setprio 1
	s_waitcnt lgkmcnt(0)
	v_mfma_f32_16x16x32_bf16 v[124:127], v[128:131], v[184:187], v[124:127]
	v_mfma_f32_16x16x32_bf16 v[120:123], v[136:139], v[184:187], v[120:123]
	v_mfma_f32_16x16x32_bf16 v[108:111], v[128:131], v[192:195], v[108:111]
	v_mfma_f32_16x16x32_bf16 v[104:107], v[136:139], v[192:195], v[104:107]
	v_mfma_f32_16x16x32_bf16 v[92:95], v[128:131], v[200:203], v[92:95]
	v_mfma_f32_16x16x32_bf16 v[88:91], v[136:139], v[200:203], v[88:91]
	v_mfma_f32_16x16x32_bf16 v[76:79], v[128:131], v[208:211], v[76:79]
	v_mfma_f32_16x16x32_bf16 v[72:75], v[136:139], v[208:211], v[72:75]
	v_mfma_f32_16x16x32_bf16 v[124:127], v[132:135], v[188:191], v[124:127]
	v_mfma_f32_16x16x32_bf16 v[120:123], v[140:143], v[188:191], v[120:123]
	v_mfma_f32_16x16x32_bf16 v[108:111], v[132:135], v[196:199], v[108:111]
	v_mfma_f32_16x16x32_bf16 v[104:107], v[140:143], v[196:199], v[104:107]
	v_mfma_f32_16x16x32_bf16 v[92:95], v[132:135], v[204:207], v[92:95]
	v_mfma_f32_16x16x32_bf16 v[88:91], v[140:143], v[204:207], v[88:91]
	v_mfma_f32_16x16x32_bf16 v[76:79], v[132:135], v[212:215], v[76:79]
	v_mfma_f32_16x16x32_bf16 v[72:75], v[140:143], v[212:215], v[72:75]
	s_nop 0
	s_nop 0
	v_mfma_f32_16x16x32_bf16 v[116:119], v[160:163], v[184:187], v[116:119]
	v_mfma_f32_16x16x32_bf16 v[112:115], v[176:179], v[184:187], v[112:115]
	v_mfma_f32_16x16x32_bf16 v[100:103], v[160:163], v[192:195], v[100:103]
	v_mfma_f32_16x16x32_bf16 v[96:99], v[176:179], v[192:195], v[96:99]
	v_mfma_f32_16x16x32_bf16 v[84:87], v[160:163], v[200:203], v[84:87]
	v_mfma_f32_16x16x32_bf16 v[80:83], v[176:179], v[200:203], v[80:83]
	v_mfma_f32_16x16x32_bf16 v[68:71], v[160:163], v[208:211], v[68:71]
	v_mfma_f32_16x16x32_bf16 v[64:67], v[176:179], v[208:211], v[64:67]
	v_mfma_f32_16x16x32_bf16 v[116:119], v[170:173], v[188:191], v[116:119]
	v_mfma_f32_16x16x32_bf16 v[112:115], v[180:183], v[188:191], v[112:115]
	v_mfma_f32_16x16x32_bf16 v[100:103], v[170:173], v[196:199], v[100:103]
	v_mfma_f32_16x16x32_bf16 v[96:99], v[180:183], v[196:199], v[96:99]
	v_mfma_f32_16x16x32_bf16 v[84:87], v[170:173], v[204:207], v[84:87]
	v_mfma_f32_16x16x32_bf16 v[80:83], v[180:183], v[204:207], v[80:83]
	v_mfma_f32_16x16x32_bf16 v[68:71], v[170:173], v[212:215], v[68:71]
	v_mfma_f32_16x16x32_bf16 v[64:67], v[180:183], v[212:215], v[64:67]
	s_setprio 0
	s_barrier
	s_add_u32 s100, s38, 0xfffc0080
	s_addc_u32 s101, s39, -1
	s_add_u32 s98, s36, 0x80
	s_addc_u32 s99, s37, 0
	s_add_i32 s38, s64, s73
	s_mov_b32 m0, s38
	ds_read_b128 v[184:187], v169 offset:49152
	ds_read_b128 v[188:191], v169 offset:50176
	ds_read_b128 v[192:195], v169 offset:51200
	ds_read_b128 v[196:199], v169 offset:52224
	ds_read_b128 v[200:203], v169 offset:53248
	ds_read_b128 v[204:207], v169 offset:54272
	ds_read_b128 v[208:211], v169 offset:55296
	ds_read_b128 v[212:215], v169 offset:56320
	global_load_lds_dwordx4 v146, s[98:99]
	s_add_i32 m0, s38, 0x2000
	s_add_u32 s36, s36, 0x40080
	s_addc_u32 s37, s37, 0
	s_add_i32 s38, s65, s73
	global_load_lds_dwordx4 v150, s[98:99]
	s_mov_b32 m0, s38
	s_nop 0
	global_load_lds_dwordx4 v146, s[36:37]
	s_add_i32 m0, s38, 0x2000
	s_nop 0
	global_load_lds_dwordx4 v150, s[36:37]
	s_mov_b32 m0, s54
	s_nop 0
	global_load_lds_dwordx4 v144, s[100:101]
	s_mov_b32 m0, s55
	s_nop 0
	global_load_lds_dwordx4 v148, s[100:101]
	s_waitcnt vmcnt(8)
	s_waitcnt lgkmcnt(0)
	s_barrier
	s_setprio 1
	s_waitcnt lgkmcnt(0)
	v_mfma_f32_16x16x32_bf16 v[60:63], v[128:131], v[184:187], v[60:63]
	v_mfma_f32_16x16x32_bf16 v[56:59], v[136:139], v[184:187], v[56:59]
	v_mfma_f32_16x16x32_bf16 v[44:47], v[128:131], v[192:195], v[44:47]
	v_mfma_f32_16x16x32_bf16 v[40:43], v[136:139], v[192:195], v[40:43]
	v_mfma_f32_16x16x32_bf16 v[28:31], v[128:131], v[200:203], v[28:31]
	v_mfma_f32_16x16x32_bf16 v[24:27], v[136:139], v[200:203], v[24:27]
	v_mfma_f32_16x16x32_bf16 v[12:15], v[128:131], v[208:211], v[12:15]
	v_mfma_f32_16x16x32_bf16 v[8:11], v[136:139], v[208:211], v[8:11]
	v_mfma_f32_16x16x32_bf16 v[60:63], v[132:135], v[188:191], v[60:63]
	v_mfma_f32_16x16x32_bf16 v[56:59], v[140:143], v[188:191], v[56:59]
	v_mfma_f32_16x16x32_bf16 v[44:47], v[132:135], v[196:199], v[44:47]
	v_mfma_f32_16x16x32_bf16 v[40:43], v[140:143], v[196:199], v[40:43]
	v_mfma_f32_16x16x32_bf16 v[28:31], v[132:135], v[204:207], v[28:31]
	v_mfma_f32_16x16x32_bf16 v[24:27], v[140:143], v[204:207], v[24:27]
	v_mfma_f32_16x16x32_bf16 v[12:15], v[132:135], v[212:215], v[12:15]
	v_mfma_f32_16x16x32_bf16 v[8:11], v[140:143], v[212:215], v[8:11]
	s_nop 0
	s_nop 0
	v_mfma_f32_16x16x32_bf16 v[52:55], v[160:163], v[184:187], v[52:55]
	v_mfma_f32_16x16x32_bf16 v[48:51], v[176:179], v[184:187], v[48:51]
	v_mfma_f32_16x16x32_bf16 v[36:39], v[160:163], v[192:195], v[36:39]
	v_mfma_f32_16x16x32_bf16 v[32:35], v[176:179], v[192:195], v[32:35]
	v_mfma_f32_16x16x32_bf16 v[20:23], v[160:163], v[200:203], v[20:23]
	v_mfma_f32_16x16x32_bf16 v[16:19], v[176:179], v[200:203], v[16:19]
	v_mfma_f32_16x16x32_bf16 v[4:7], v[160:163], v[208:211], v[4:7]
	v_mfma_f32_16x16x32_bf16 v[0:3], v[176:179], v[208:211], v[0:3]
	v_mfma_f32_16x16x32_bf16 v[52:55], v[170:173], v[188:191], v[52:55]
	v_mfma_f32_16x16x32_bf16 v[48:51], v[180:183], v[188:191], v[48:51]
	v_mfma_f32_16x16x32_bf16 v[36:39], v[170:173], v[196:199], v[36:39]
	v_mfma_f32_16x16x32_bf16 v[32:35], v[180:183], v[196:199], v[32:35]
	v_mfma_f32_16x16x32_bf16 v[20:23], v[170:173], v[204:207], v[20:23]
	v_mfma_f32_16x16x32_bf16 v[16:19], v[180:183], v[204:207], v[16:19]
	v_mfma_f32_16x16x32_bf16 v[4:7], v[170:173], v[212:215], v[4:7]
	v_mfma_f32_16x16x32_bf16 v[0:3], v[180:183], v[212:215], v[0:3]
	s_setprio 0
	s_barrier
	s_add_i32 s59, s59, 2
	s_add_u32 s34, s34, 0x100
	s_addc_u32 s35, s35, 0
	s_add_u32 s57, s57, 0x100
	s_addc_u32 s58, s58, 0
	s_cmp_gt_u32 s59, 13
	s_cbranch_scc0 .LBB0_553
	s_and_b64 vcc, exec, s[12:13]
	s_cbranch_vccz .LBB0_556
	s_barrier

; #define PG8_STAGE(bufoff, gbase, voff) do { _Pragma("unroll") for (int _i = 0; _i < 2; ++_i) \
;         __builtin_amdgcn_global_load_lds((const unsigned*)((const char*)(gbase) + (voff)[_i]), (LAS unsigned*)(lds + (bufoff) + ldsw + _i * 8192), 16, 0, 0); } while (0)
; #define PG8_LDA(dst, b, h) do { _Pragma("unroll") for (int m = 0; m < 4; ++m) _Pragma("unroll") for (int k = 0; k < 2; ++k) dst[m][k] = *(const LAS bf16x8*)(lds + PG8_SA(b, h) + aoff + m * 2048 + k * 1024); } while (0)
; #define PG8_LDB(dst, b, h) do { _Pragma("unroll") for (int n = 0; n < 2; ++n) _Pragma("unroll") for (int k = 0; k < 2; ++k) dst[n][k] = *(const LAS bf16x8*)(lds + PG8_SB(b, h) + boff + n * 2048 + k * 1024); } while (0)
; #define PG8_MMA(ai, bj, At, Bt) do { __builtin_amdgcn_s_setprio(1); _Pragma("unroll") for (int m = 0; m < 4; ++m) _Pragma("unroll") for (int n = 0; n < 2; ++n) _Pragma("unroll") for (int k = 0; k < 2; ++k) \
;         acc[ai][bj][m][n] = __builtin_amdgcn_mfma_f32_16x16x32_bf16(Bt[n][k], At[m][k], acc[ai][bj][m][n], 0, 0, 0); __builtin_amdgcn_s_setprio(0); } while (0)
; #define PG8_WAIT_V(n) asm volatile("s_waitcnt vmcnt(" #n ")" ::: "memory")
; #define PG8_WAIT_L(n) asm volatile("s_waitcnt lgkmcnt(" #n ")" ::: "memory")
; #define PG8_BAR __builtin_amdgcn_s_barrier()
; template <class Epi, class Sched, bool ALIGN_EPI, bool SP2>
; __device__ __forceinline__ void gemm_phase(LAS unsigned char* lds, const Gemm g, const Sched& S, const Epi& E) {
;     ...
;         for (int t = 0; t < nt; t += 2) {
;             const bool last = (t == nt - 2);
;             const char* a1 = cA + (size_t)(t + 1) * kstep;
;             const char* a2 = last ? nA : cA + (size_t)(t + 2) * kstep; const char* b2 = last ? nB : cB + (size_t)(t + 2) * kstep;
;             const char* a3 = a2 + kstep; const char* b3 = b2 + kstep;
;             if constexpr (SP2) {
;             PG8_LDB(B0, 0, 0); PG8_LDB(B1, 0, 1); PG8_SCHED; PG8_LDA(At, 0, 0); PG8_STAGE(PG8_SA(1, 1), a1 + hstep, voffA);
;             PG8_WAIT_V(8); PG8_WAIT_L(0); PG8_BAR; PG8_MMA(0, 0, At, B0); PG8_MMA(0, 1, At, B1); PG8_BAR; PG8_SCHED;
;             PG8_LDA(At, 0, 1); PG8_STAGE(PG8_SB(0, 0), b2, voffB); PG8_STAGE(PG8_SB(0, 1), b2 + hstep, voffB); PG8_STAGE(PG8_SA(0, 0), a2, voffA);
;             PG8_WAIT_V(8); PG8_WAIT_L(0); PG8_BAR; PG8_MMA(1, 0, At, B0); PG8_MMA(1, 1, At, B1); PG8_BAR; PG8_SCHED;
.LBB0_683:
	s_add_u32 s26, s24, 0xfffc0080
	s_addc_u32 s27, s25, -1
	s_cmp_eq_u32 s52, 12
	s_cselect_b32 s29, s15, s27
	s_cselect_b32 s28, s48, s26
	s_cselect_b32 s27, s17, s51
	s_cselect_b32 s26, s49, s50
	s_add_i32 m0, s23, 0xc000
	s_nop 0
	global_load_lds_dwordx4 v136, s[24:25]
	s_add_i32 m0, s23, 0xe000
	s_nop 0
	global_load_lds_dwordx4 v138, s[24:25]
	ds_read_b128 v[150:153], v147
	ds_read_b128 v[154:157], v147 offset:1024
	ds_read_b128 v[158:161], v147 offset:2048
	ds_read_b128 v[162:165], v147 offset:3072
	ds_read_b128 v[166:169], v148
	ds_read_b128 v[170:173], v148 offset:1024
	ds_read_b128 v[176:179], v148 offset:2048
	ds_read_b128 v[180:183], v148 offset:3072
	ds_read_b128 v[184:187], v149
	ds_read_b128 v[188:191], v149 offset:1024
	ds_read_b128 v[192:195], v149 offset:2048
	ds_read_b128 v[196:199], v149 offset:3072
	ds_read_b128 v[200:203], v149 offset:4096
	ds_read_b128 v[204:207], v149 offset:5120
	ds_read_b128 v[208:211], v149 offset:6144
	ds_read_b128 v[212:215], v149 offset:7168
	s_waitcnt vmcnt(8)
	s_waitcnt lgkmcnt(0)
	s_barrier
	s_setprio 1
	s_waitcnt lgkmcnt(0)
	v_mfma_f32_16x16x32_bf16 v[124:127], v[150:153], v[184:187], v[124:127]
	v_mfma_f32_16x16x32_bf16 v[120:123], v[158:161], v[184:187], v[120:123]
	v_mfma_f32_16x16x32_bf16 v[108:111], v[150:153], v[192:195], v[108:111]
	v_mfma_f32_16x16x32_bf16 v[104:107], v[158:161], v[192:195], v[104:107]
	v_mfma_f32_16x16x32_bf16 v[92:95], v[150:153], v[200:203], v[92:95]
	v_mfma_f32_16x16x32_bf16 v[88:91], v[158:161], v[200:203], v[88:91]
	v_mfma_f32_16x16x32_bf16 v[76:79], v[150:153], v[208:211], v[76:79]
	v_mfma_f32_16x16x32_bf16 v[72:75], v[158:161], v[208:211], v[72:75]
	v_mfma_f32_16x16x32_bf16 v[124:127], v[154:157], v[188:191], v[124:127]
	v_mfma_f32_16x16x32_bf16 v[120:123], v[162:165], v[188:191], v[120:123]
	v_mfma_f32_16x16x32_bf16 v[108:111], v[154:157], v[196:199], v[108:111]
	v_mfma_f32_16x16x32_bf16 v[104:107], v[162:165], v[196:199], v[104:107]
	v_mfma_f32_16x16x32_bf16 v[92:95], v[154:157], v[204:207], v[92:95]
	v_mfma_f32_16x16x32_bf16 v[88:91], v[162:165], v[204:207], v[88:91]
	v_mfma_f32_16x16x32_bf16 v[76:79], v[154:157], v[212:215], v[76:79]
	v_mfma_f32_16x16x32_bf16 v[72:75], v[162:165], v[212:215], v[72:75]
	s_nop 0
	s_nop 0
	v_mfma_f32_16x16x32_bf16 v[116:119], v[166:169], v[184:187], v[116:119]
	v_mfma_f32_16x16x32_bf16 v[112:115], v[176:179], v[184:187], v[112:115]
	v_mfma_f32_16x16x32_bf16 v[100:103], v[166:169], v[192:195], v[100:103]
	v_mfma_f32_16x16x32_bf16 v[96:99], v[176:179], v[192:195], v[96:99]
	v_mfma_f32_16x16x32_bf16 v[84:87], v[166:169], v[200:203], v[84:87]
	v_mfma_f32_16x16x32_bf16 v[80:83], v[176:179], v[200:203], v[80:83]
	v_mfma_f32_16x16x32_bf16 v[68:71], v[166:169], v[208:211], v[68:71]
	v_mfma_f32_16x16x32_bf16 v[64:67], v[176:179], v[208:211], v[64:67]
	v_mfma_f32_16x16x32_bf16 v[116:119], v[170:173], v[188:191], v[116:119]
	v_mfma_f32_16x16x32_bf16 v[112:115], v[180:183], v[188:191], v[112:115]
	v_mfma_f32_16x16x32_bf16 v[100:103], v[170:173], v[196:199], v[100:103]
	v_mfma_f32_16x16x32_bf16 v[96:99], v[180:183], v[196:199], v[96:99]
	v_mfma_f32_16x16x32_bf16 v[84:87], v[170:173], v[204:207], v[84:87]
	v_mfma_f32_16x16x32_bf16 v[80:83], v[180:183], v[204:207], v[80:83]
	v_mfma_f32_16x16x32_bf16 v[68:71], v[170:173], v[212:215], v[68:71]
	v_mfma_f32_16x16x32_bf16 v[64:67], v[180:183], v[212:215], v[64:67]
	s_setprio 0
	s_barrier
	s_add_i32 s53, s44, s30
	s_mov_b32 m0, s53
	s_nop 0
	global_load_lds_dwordx4 v132, s[26:27]
	s_add_i32 m0, s53, 0x2000
	s_add_u32 s54, s26, 0x40000
	s_addc_u32 s55, s27, 0
	s_add_i32 s53, s45, s30
	global_load_lds_dwordx4 v128, s[26:27]
	s_mov_b32 m0, s53
	s_nop 0
	global_load_lds_dwordx4 v132, s[54:55]
	s_add_i32 m0, s53, 0x2000
	s_nop 0
	global_load_lds_dwordx4 v128, s[54:55]
	s_mov_b32 m0, s23
	s_nop 0
	global_load_lds_dwordx4 v134, s[28:29]
	s_mov_b32 m0, s34
	s_nop 0
	global_load_lds_dwordx4 v130, s[28:29]
	ds_read_b128 v[184:187], v149 offset:16384
	ds_read_b128 v[188:191], v149 offset:17408
	ds_read_b128 v[192:195], v149 offset:18432
	ds_read_b128 v[196:199], v149 offset:19456
	ds_read_b128 v[200:203], v149 offset:20480
	ds_read_b128 v[204:207], v149 offset:21504
	ds_read_b128 v[208:211], v149 offset:22528
	ds_read_b128 v[212:215], v149 offset:23552
	s_waitcnt vmcnt(8)
	s_waitcnt lgkmcnt(0)
	s_barrier
	s_setprio 1
	s_waitcnt lgkmcnt(0)
	v_mfma_f32_16x16x32_bf16 v[60:63], v[150:153], v[184:187], v[60:63]
	v_mfma_f32_16x16x32_bf16 v[56:59], v[158:161], v[184:187], v[56:59]
	v_mfma_f32_16x16x32_bf16 v[44:47], v[150:153], v[192:195], v[44:47]
	v_mfma_f32_16x16x32_bf16 v[40:43], v[158:161], v[192:195], v[40:43]
	v_mfma_f32_16x16x32_bf16 v[28:31], v[150:153], v[200:203], v[28:31]
	v_mfma_f32_16x16x32_bf16 v[24:27], v[158:161], v[200:203], v[24:27]
	v_mfma_f32_16x16x32_bf16 v[12:15], v[150:153], v[208:211], v[12:15]
	v_mfma_f32_16x16x32_bf16 v[8:11], v[158:161], v[208:211], v[8:11]
	v_mfma_f32_16x16x32_bf16 v[60:63], v[154:157], v[188:191], v[60:63]
	v_mfma_f32_16x16x32_bf16 v[56:59], v[162:165], v[188:191], v[56:59]
	v_mfma_f32_16x16x32_bf16 v[44:47], v[154:157], v[196:199], v[44:47]
	v_mfma_f32_16x16x32_bf16 v[40:43], v[162:165], v[196:199], v[40:43]
	v_mfma_f32_16x16x32_bf16 v[28:31], v[154:157], v[204:207], v[28:31]
	v_mfma_f32_16x16x32_bf16 v[24:27], v[162:165], v[204:207], v[24:27]
	v_mfma_f32_16x16x32_bf16 v[12:15], v[154:157], v[212:215], v[12:15]
	v_mfma_f32_16x16x32_bf16 v[8:11], v[162:165], v[212:215], v[8:11]
	s_nop 0
	s_nop 0
	v_mfma_f32_16x16x32_bf16 v[52:55], v[166:169], v[184:187], v[52:55]
	v_mfma_f32_16x16x32_bf16 v[48:51], v[176:179], v[184:187], v[48:51]
	v_mfma_f32_16x16x32_bf16 v[36:39], v[166:169], v[192:195], v[36:39]
	v_mfma_f32_16x16x32_bf16 v[32:35], v[176:179], v[192:195], v[32:35]
	v_mfma_f32_16x16x32_bf16 v[20:23], v[166:169], v[200:203], v[20:23]
	v_mfma_f32_16x16x32_bf16 v[16:19], v[176:179], v[200:203], v[16:19]
	v_mfma_f32_16x16x32_bf16 v[4:7], v[166:169], v[208:211], v[4:7]
	v_mfma_f32_16x16x32_bf16 v[0:3], v[176:179], v[208:211], v[0:3]
	v_mfma_f32_16x16x32_bf16 v[52:55], v[170:173], v[188:191], v[52:55]
	v_mfma_f32_16x16x32_bf16 v[48:51], v[180:183], v[188:191], v[48:51]
	v_mfma_f32_16x16x32_bf16 v[36:39], v[170:173], v[196:199], v[36:39]
	v_mfma_f32_16x16x32_bf16 v[32:35], v[180:183], v[196:199], v[32:35]
	v_mfma_f32_16x16x32_bf16 v[20:23], v[170:173], v[204:207], v[20:23]
	v_mfma_f32_16x16x32_bf16 v[16:19], v[180:183], v[204:207], v[16:19]
	v_mfma_f32_16x16x32_bf16 v[4:7], v[170:173], v[212:215], v[4:7]
	v_mfma_f32_16x16x32_bf16 v[0:3], v[180:183], v[212:215], v[0:3]
	s_setprio 0
	s_barrier
; #define PG8_STAGE(bufoff, gbase, voff) do { _Pragma("unroll") for (int _i = 0; _i < 2; ++_i) \
;         __builtin_amdgcn_global_load_lds((const unsigned*)((const char*)(gbase) + (voff)[_i]), (LAS unsigned*)(lds + (bufoff) + ldsw + _i * 8192), 16, 0, 0); } while (0)
; #define PG8_LDA(dst, b, h) do { _Pragma("unroll") for (int m = 0; m < 4; ++m) _Pragma("unroll") for (int k = 0; k < 2; ++k) dst[m][k] = *(const LAS bf16x8*)(lds + PG8_SA(b, h) + aoff + m * 2048 + k * 1024); } while (0)
; #define PG8_LDB(dst, b, h) do { _Pragma("unroll") for (int n = 0; n < 2; ++n) _Pragma("unroll") for (int k = 0; k < 2; ++k) dst[n][k] = *(const LAS bf16x8*)(lds + PG8_SB(b, h) + boff + n * 2048 + k * 1024); } while (0)
; #define PG8_MMA(ai, bj, At, Bt) do { __builtin_amdgcn_s_setprio(1); _Pragma("unroll") for (int m = 0; m < 4; ++m) _Pragma("unroll") for (int n = 0; n < 2; ++n) _Pragma("unroll") for (int k = 0; k < 2; ++k) \
;         acc[ai][bj][m][n] = __builtin_amdgcn_mfma_f32_16x16x32_bf16(Bt[n][k], At[m][k], acc[ai][bj][m][n], 0, 0, 0); __builtin_amdgcn_s_setprio(0); } while (0)
; #define PG8_WAIT_V(n) asm volatile("s_waitcnt vmcnt(" #n ")" ::: "memory")
; #define PG8_WAIT_L(n) asm volatile("s_waitcnt lgkmcnt(" #n ")" ::: "memory")
; #define PG8_BAR __builtin_amdgcn_s_barrier()
; #define PG8_SCHED __builtin_amdgcn_sched_barrier(0)
; template <class Epi, class Sched, bool ALIGN_EPI, bool SP2>
; __device__ __forceinline__ void gemm_phase(LAS unsigned char* lds, const Gemm g, const Sched& S, const Epi& E) {
;     ...
;             PG8_LDB(B0, 1, 0); PG8_LDB(B1, 1, 1); PG8_SCHED; PG8_LDA(At, 1, 0); PG8_STAGE(PG8_SA(0, 1), a2 + hstep, voffA);
;             PG8_WAIT_V(8); PG8_WAIT_L(0); PG8_BAR; PG8_MMA(0, 0, At, B0); PG8_MMA(0, 1, At, B1); PG8_BAR; PG8_SCHED;
;             PG8_LDA(At, 1, 1); PG8_STAGE(PG8_SB(1, 0), b3, voffB); PG8_STAGE(PG8_SB(1, 1), b3 + hstep, voffB); PG8_STAGE(PG8_SA(1, 0), a3, voffA);
;             PG8_WAIT_V(8); PG8_WAIT_L(0); PG8_BAR; PG8_MMA(1, 0, At, B0); PG8_MMA(1, 1, At, B1); PG8_BAR; PG8_SCHED;
;     ...
;         }
;         if constexpr (ALIGN_EPI) { if (wr == 0) PG8_BAR; }
	s_add_i32 s53, 0, 0x18000
	s_add_i32 s54, 0, 0x1c000
	v_add_u32_e32 v162, s53, v145
	v_add_u32_e32 v174, s54, v145
	s_add_u32 s28, s28, 0x40000
	s_addc_u32 s29, s29, 0
	s_mov_b32 m0, s35
	s_nop 0
	global_load_lds_dwordx4 v134, s[28:29]
	s_mov_b32 m0, s36
	s_nop 0
	global_load_lds_dwordx4 v130, s[28:29]
	ds_read_b128 v[150:153], v162
	ds_read_b128 v[154:157], v162 offset:1024
	ds_read_b128 v[158:161], v162 offset:2048
	ds_read_b128 v[162:165], v162 offset:3072
	ds_read_b128 v[166:169], v174
	ds_read_b128 v[170:173], v174 offset:1024
	ds_read_b128 v[176:179], v174 offset:2048
	ds_read_b128 v[180:183], v174 offset:3072
	ds_read_b128 v[184:187], v149 offset:32768
	ds_read_b128 v[188:191], v149 offset:33792
	ds_read_b128 v[192:195], v149 offset:34816
	ds_read_b128 v[196:199], v149 offset:35840
	ds_read_b128 v[200:203], v149 offset:36864
	ds_read_b128 v[204:207], v149 offset:37888
	ds_read_b128 v[208:211], v149 offset:38912
	ds_read_b128 v[212:215], v149 offset:39936
	s_waitcnt vmcnt(8)
	s_waitcnt lgkmcnt(0)
	s_barrier
	s_setprio 1
	s_waitcnt lgkmcnt(0)
	v_mfma_f32_16x16x32_bf16 v[124:127], v[150:153], v[184:187], v[124:127]
	v_mfma_f32_16x16x32_bf16 v[120:123], v[158:161], v[184:187], v[120:123]
	v_mfma_f32_16x16x32_bf16 v[108:111], v[150:153], v[192:195], v[108:111]
	v_mfma_f32_16x16x32_bf16 v[104:107], v[158:161], v[192:195], v[104:107]
	v_mfma_f32_16x16x32_bf16 v[92:95], v[150:153], v[200:203], v[92:95]
	v_mfma_f32_16x16x32_bf16 v[88:91], v[158:161], v[200:203], v[88:91]
	v_mfma_f32_16x16x32_bf16 v[76:79], v[150:153], v[208:211], v[76:79]
	v_mfma_f32_16x16x32_bf16 v[72:75], v[158:161], v[208:211], v[72:75]
	v_mfma_f32_16x16x32_bf16 v[124:127], v[154:157], v[188:191], v[124:127]
	v_mfma_f32_16x16x32_bf16 v[120:123], v[162:165], v[188:191], v[120:123]
	v_mfma_f32_16x16x32_bf16 v[108:111], v[154:157], v[196:199], v[108:111]
	v_mfma_f32_16x16x32_bf16 v[104:107], v[162:165], v[196:199], v[104:107]
	v_mfma_f32_16x16x32_bf16 v[92:95], v[154:157], v[204:207], v[92:95]
	v_mfma_f32_16x16x32_bf16 v[88:91], v[162:165], v[204:207], v[88:91]
	v_mfma_f32_16x16x32_bf16 v[76:79], v[154:157], v[212:215], v[76:79]
	v_mfma_f32_16x16x32_bf16 v[72:75], v[162:165], v[212:215], v[72:75]
	s_nop 0
	s_nop 0
	v_mfma_f32_16x16x32_bf16 v[116:119], v[166:169], v[184:187], v[116:119]
	v_mfma_f32_16x16x32_bf16 v[112:115], v[176:179], v[184:187], v[112:115]
	v_mfma_f32_16x16x32_bf16 v[100:103], v[166:169], v[192:195], v[100:103]
	v_mfma_f32_16x16x32_bf16 v[96:99], v[176:179], v[192:195], v[96:99]
	v_mfma_f32_16x16x32_bf16 v[84:87], v[166:169], v[200:203], v[84:87]
	v_mfma_f32_16x16x32_bf16 v[80:83], v[176:179], v[200:203], v[80:83]
	v_mfma_f32_16x16x32_bf16 v[68:71], v[166:169], v[208:211], v[68:71]
	v_mfma_f32_16x16x32_bf16 v[64:67], v[176:179], v[208:211], v[64:67]
	v_mfma_f32_16x16x32_bf16 v[116:119], v[170:173], v[188:191], v[116:119]
	v_mfma_f32_16x16x32_bf16 v[112:115], v[180:183], v[188:191], v[112:115]
	v_mfma_f32_16x16x32_bf16 v[100:103], v[170:173], v[196:199], v[100:103]
	v_mfma_f32_16x16x32_bf16 v[96:99], v[180:183], v[196:199], v[96:99]
	v_mfma_f32_16x16x32_bf16 v[84:87], v[170:173], v[204:207], v[84:87]
	v_mfma_f32_16x16x32_bf16 v[80:83], v[180:183], v[204:207], v[80:83]
	v_mfma_f32_16x16x32_bf16 v[68:71], v[170:173], v[212:215], v[68:71]
	v_mfma_f32_16x16x32_bf16 v[64:67], v[180:183], v[212:215], v[64:67]
	s_setprio 0
	s_barrier
	s_add_u32 s100, s28, 0xfffc0080
	s_addc_u32 s101, s29, -1
	s_add_u32 s98, s26, 0x80
	s_addc_u32 s99, s27, 0
	s_add_i32 s28, s53, s30
	s_mov_b32 m0, s28
	s_nop 0
	global_load_lds_dwordx4 v132, s[98:99]
	s_add_i32 m0, s28, 0x2000
	s_add_u32 s26, s26, 0x40080
	s_addc_u32 s27, s27, 0
	s_add_i32 s28, s54, s30
	global_load_lds_dwordx4 v128, s[98:99]
	s_mov_b32 m0, s28
	s_nop 0
	global_load_lds_dwordx4 v132, s[26:27]
	s_add_i32 m0, s28, 0x2000
	s_nop 0
	global_load_lds_dwordx4 v128, s[26:27]
	s_mov_b32 m0, s38
	s_nop 0
	global_load_lds_dwordx4 v134, s[100:101]
	s_mov_b32 m0, s39
	s_nop 0
	global_load_lds_dwordx4 v130, s[100:101]
	ds_read_b128 v[184:187], v149 offset:49152
	ds_read_b128 v[188:191], v149 offset:50176
	ds_read_b128 v[192:195], v149 offset:51200
	ds_read_b128 v[196:199], v149 offset:52224
	ds_read_b128 v[200:203], v149 offset:53248
	ds_read_b128 v[204:207], v149 offset:54272
	ds_read_b128 v[208:211], v149 offset:55296
	ds_read_b128 v[212:215], v149 offset:56320
	s_waitcnt vmcnt(8)
	s_waitcnt lgkmcnt(0)
	s_barrier
	s_setprio 1
	s_waitcnt lgkmcnt(0)
	v_mfma_f32_16x16x32_bf16 v[60:63], v[150:153], v[184:187], v[60:63]
	v_mfma_f32_16x16x32_bf16 v[56:59], v[158:161], v[184:187], v[56:59]
	v_mfma_f32_16x16x32_bf16 v[44:47], v[150:153], v[192:195], v[44:47]
	v_mfma_f32_16x16x32_bf16 v[40:43], v[158:161], v[192:195], v[40:43]
	v_mfma_f32_16x16x32_bf16 v[28:31], v[150:153], v[200:203], v[28:31]
	v_mfma_f32_16x16x32_bf16 v[24:27], v[158:161], v[200:203], v[24:27]
	v_mfma_f32_16x16x32_bf16 v[12:15], v[150:153], v[208:211], v[12:15]
	v_mfma_f32_16x16x32_bf16 v[8:11], v[158:161], v[208:211], v[8:11]
	v_mfma_f32_16x16x32_bf16 v[60:63], v[154:157], v[188:191], v[60:63]
	v_mfma_f32_16x16x32_bf16 v[56:59], v[162:165], v[188:191], v[56:59]
	v_mfma_f32_16x16x32_bf16 v[44:47], v[154:157], v[196:199], v[44:47]
	v_mfma_f32_16x16x32_bf16 v[40:43], v[162:165], v[196:199], v[40:43]
	v_mfma_f32_16x16x32_bf16 v[28:31], v[154:157], v[204:207], v[28:31]
	v_mfma_f32_16x16x32_bf16 v[24:27], v[162:165], v[204:207], v[24:27]
	v_mfma_f32_16x16x32_bf16 v[12:15], v[154:157], v[212:215], v[12:15]
	v_mfma_f32_16x16x32_bf16 v[8:11], v[162:165], v[212:215], v[8:11]
	s_nop 0
	s_nop 0
	v_mfma_f32_16x16x32_bf16 v[52:55], v[166:169], v[184:187], v[52:55]
	v_mfma_f32_16x16x32_bf16 v[48:51], v[176:179], v[184:187], v[48:51]
	v_mfma_f32_16x16x32_bf16 v[36:39], v[166:169], v[192:195], v[36:39]
	v_mfma_f32_16x16x32_bf16 v[32:35], v[176:179], v[192:195], v[32:35]
	v_mfma_f32_16x16x32_bf16 v[20:23], v[166:169], v[200:203], v[20:23]
	v_mfma_f32_16x16x32_bf16 v[16:19], v[176:179], v[200:203], v[16:19]
	v_mfma_f32_16x16x32_bf16 v[4:7], v[166:169], v[208:211], v[4:7]
	v_mfma_f32_16x16x32_bf16 v[0:3], v[176:179], v[208:211], v[0:3]
	v_mfma_f32_16x16x32_bf16 v[52:55], v[170:173], v[188:191], v[52:55]
	v_mfma_f32_16x16x32_bf16 v[48:51], v[180:183], v[188:191], v[48:51]
	v_mfma_f32_16x16x32_bf16 v[36:39], v[170:173], v[196:199], v[36:39]
	v_mfma_f32_16x16x32_bf16 v[32:35], v[180:183], v[196:199], v[32:35]
	v_mfma_f32_16x16x32_bf16 v[20:23], v[170:173], v[204:207], v[20:23]
	v_mfma_f32_16x16x32_bf16 v[16:19], v[180:183], v[204:207], v[16:19]
	v_mfma_f32_16x16x32_bf16 v[4:7], v[170:173], v[212:215], v[4:7]
	v_mfma_f32_16x16x32_bf16 v[0:3], v[180:183], v[212:215], v[0:3]
	s_setprio 0
	s_barrier
	s_add_i32 s52, s52, 2
	s_add_u32 s24, s24, 0x100
	s_addc_u32 s25, s25, 0
	s_add_u32 s50, s50, 0x100
	s_addc_u32 s51, s51, 0
	s_cmp_gt_u32 s52, 13
	s_cbranch_scc0 .LBB0_683
	s_and_b64 vcc, exec, s[12:13]
	s_cbranch_vccz .LBB0_686
	s_barrier

; #define PG8_STAGE(bufoff, gbase, voff) do { _Pragma("unroll") for (int _i = 0; _i < 2; ++_i) \
;         __builtin_amdgcn_global_load_lds((const unsigned*)((const char*)(gbase) + (voff)[_i]), (LAS unsigned*)(lds + (bufoff) + ldsw + _i * 8192), 16, 0, 0); } while (0)
; #define PG8_LDA(dst, b, h) do { _Pragma("unroll") for (int m = 0; m < 4; ++m) _Pragma("unroll") for (int k = 0; k < 2; ++k) dst[m][k] = *(const LAS bf16x8*)(lds + PG8_SA(b, h) + aoff + m * 2048 + k * 1024); } while (0)
; #define PG8_LDB(dst, b, h) do { _Pragma("unroll") for (int n = 0; n < 2; ++n) _Pragma("unroll") for (int k = 0; k < 2; ++k) dst[n][k] = *(const LAS bf16x8*)(lds + PG8_SB(b, h) + boff + n * 2048 + k * 1024); } while (0)
; #define PG8_MMA(ai, bj, At, Bt) do { __builtin_amdgcn_s_setprio(1); _Pragma("unroll") for (int m = 0; m < 4; ++m) _Pragma("unroll") for (int n = 0; n < 2; ++n) _Pragma("unroll") for (int k = 0; k < 2; ++k) \
;         acc[ai][bj][m][n] = __builtin_amdgcn_mfma_f32_16x16x32_bf16(Bt[n][k], At[m][k], acc[ai][bj][m][n], 0, 0, 0); __builtin_amdgcn_s_setprio(0); } while (0)
; #define PG8_WAIT_V(n) asm volatile("s_waitcnt vmcnt(" #n ")" ::: "memory")
; #define PG8_WAIT_L(n) asm volatile("s_waitcnt lgkmcnt(" #n ")" ::: "memory")
; #define PG8_BAR __builtin_amdgcn_s_barrier()
; template <class Epi, class Sched, bool ALIGN_EPI, bool SP2>
; __device__ __forceinline__ void gemm_phase(LAS unsigned char* lds, const Gemm g, const Sched& S, const Epi& E) {
;     ...
;         for (int t = 0; t < nt; t += 2) {
;             const bool last = (t == nt - 2);
;             const char* a1 = cA + (size_t)(t + 1) * kstep;
;             const char* a2 = last ? nA : cA + (size_t)(t + 2) * kstep; const char* b2 = last ? nB : cB + (size_t)(t + 2) * kstep;
;             const char* a3 = a2 + kstep; const char* b3 = b2 + kstep;
;             if constexpr (SP2) {
;             PG8_LDB(B0, 0, 0); PG8_LDB(B1, 0, 1); PG8_SCHED; PG8_LDA(At, 0, 0); PG8_STAGE(PG8_SA(1, 1), a1 + hstep, voffA);
;             PG8_WAIT_V(8); PG8_WAIT_L(0); PG8_BAR; PG8_MMA(0, 0, At, B0); PG8_MMA(0, 1, At, B1); PG8_BAR; PG8_SCHED;
;             PG8_LDA(At, 0, 1); PG8_STAGE(PG8_SB(0, 0), b2, voffB); PG8_STAGE(PG8_SB(0, 1), b2 + hstep, voffB); PG8_STAGE(PG8_SA(0, 0), a2, voffA);
;             PG8_WAIT_V(8); PG8_WAIT_L(0); PG8_BAR; PG8_MMA(1, 0, At, B0); PG8_MMA(1, 1, At, B1); PG8_BAR; PG8_SCHED;
.LBB0_766:
	s_add_u32 s26, s24, 0x100
	s_addc_u32 s27, s25, 0
	s_cmp_eq_u32 s56, 40
	s_cselect_b32 s31, s5, s27
	s_cselect_b32 s30, s4, s26
	s_cselect_b32 s29, s23, s55
	s_cselect_b32 s28, s22, s54
	s_add_i32 m0, s37, 0xc000
	s_nop 0
	global_load_lds_dwordx4 v152, s[24:25]
	s_add_i32 m0, s37, 0xe000
	s_nop 0
	global_load_lds_dwordx4 v154, s[24:25]
	ds_read_b128 v[120:123], v169
	ds_read_b128 v[124:127], v169 offset:1024
	ds_read_b128 v[136:139], v169 offset:2048
	ds_read_b128 v[140:143], v169 offset:3072
	ds_read_b128 v[160:163], v170
	ds_read_b128 v[172:175], v170 offset:1024
	ds_read_b128 v[176:179], v170 offset:2048
	ds_read_b128 v[180:183], v170 offset:3072
	ds_read_b128 v[184:187], v171
	ds_read_b128 v[188:191], v171 offset:1024
	ds_read_b128 v[192:195], v171 offset:2048
	ds_read_b128 v[196:199], v171 offset:3072
	ds_read_b128 v[200:203], v171 offset:4096
	ds_read_b128 v[204:207], v171 offset:5120
	ds_read_b128 v[208:211], v171 offset:6144
	ds_read_b128 v[212:215], v171 offset:7168
	s_waitcnt vmcnt(8)
	s_waitcnt lgkmcnt(0)
	s_barrier
	s_setprio 1
	s_waitcnt lgkmcnt(0)
	v_mfma_f32_16x16x32_bf16 v[132:135], v[120:123], v[184:187], v[132:135]
	v_mfma_f32_16x16x32_bf16 v[128:131], v[136:139], v[184:187], v[128:131]
	v_mfma_f32_16x16x32_bf16 v[108:111], v[120:123], v[192:195], v[108:111]
	v_mfma_f32_16x16x32_bf16 v[104:107], v[136:139], v[192:195], v[104:107]
	v_mfma_f32_16x16x32_bf16 v[92:95], v[120:123], v[200:203], v[92:95]
	v_mfma_f32_16x16x32_bf16 v[88:91], v[136:139], v[200:203], v[88:91]
	v_mfma_f32_16x16x32_bf16 v[76:79], v[120:123], v[208:211], v[76:79]
	v_mfma_f32_16x16x32_bf16 v[72:75], v[136:139], v[208:211], v[72:75]
	v_mfma_f32_16x16x32_bf16 v[132:135], v[124:127], v[188:191], v[132:135]
	v_mfma_f32_16x16x32_bf16 v[128:131], v[140:143], v[188:191], v[128:131]
	v_mfma_f32_16x16x32_bf16 v[108:111], v[124:127], v[196:199], v[108:111]
	v_mfma_f32_16x16x32_bf16 v[104:107], v[140:143], v[196:199], v[104:107]
	v_mfma_f32_16x16x32_bf16 v[92:95], v[124:127], v[204:207], v[92:95]
	v_mfma_f32_16x16x32_bf16 v[88:91], v[140:143], v[204:207], v[88:91]
	v_mfma_f32_16x16x32_bf16 v[76:79], v[124:127], v[212:215], v[76:79]
	v_mfma_f32_16x16x32_bf16 v[72:75], v[140:143], v[212:215], v[72:75]
	s_nop 0
	s_nop 0
	v_mfma_f32_16x16x32_bf16 v[116:119], v[160:163], v[184:187], v[116:119]
	v_mfma_f32_16x16x32_bf16 v[112:115], v[176:179], v[184:187], v[112:115]
	v_mfma_f32_16x16x32_bf16 v[100:103], v[160:163], v[192:195], v[100:103]
	v_mfma_f32_16x16x32_bf16 v[96:99], v[176:179], v[192:195], v[96:99]
	v_mfma_f32_16x16x32_bf16 v[84:87], v[160:163], v[200:203], v[84:87]
	v_mfma_f32_16x16x32_bf16 v[80:83], v[176:179], v[200:203], v[80:83]
	v_mfma_f32_16x16x32_bf16 v[68:71], v[160:163], v[208:211], v[68:71]
	v_mfma_f32_16x16x32_bf16 v[64:67], v[176:179], v[208:211], v[64:67]
	v_mfma_f32_16x16x32_bf16 v[116:119], v[172:175], v[188:191], v[116:119]
	v_mfma_f32_16x16x32_bf16 v[112:115], v[180:183], v[188:191], v[112:115]
	v_mfma_f32_16x16x32_bf16 v[100:103], v[172:175], v[196:199], v[100:103]
	v_mfma_f32_16x16x32_bf16 v[96:99], v[180:183], v[196:199], v[96:99]
	v_mfma_f32_16x16x32_bf16 v[84:87], v[172:175], v[204:207], v[84:87]
	v_mfma_f32_16x16x32_bf16 v[80:83], v[180:183], v[204:207], v[80:83]
	v_mfma_f32_16x16x32_bf16 v[68:71], v[172:175], v[212:215], v[68:71]
	v_mfma_f32_16x16x32_bf16 v[64:67], v[180:183], v[212:215], v[64:67]
	s_setprio 0
	s_barrier
	s_add_i32 s24, s48, s36
	s_mov_b32 m0, s24
	s_nop 0
	global_load_lds_dwordx4 v146, s[28:29]
	s_add_i32 m0, s24, 0x2000
	s_add_u32 s24, s28, 0xb0000
	s_addc_u32 s25, s29, 0
	s_add_i32 s57, s49, s36
	global_load_lds_dwordx4 v150, s[28:29]
	s_mov_b32 m0, s57
	s_nop 0
	global_load_lds_dwordx4 v146, s[24:25]
	s_add_i32 m0, s57, 0x2000
	s_nop 0
	global_load_lds_dwordx4 v150, s[24:25]
	s_mov_b32 m0, s37
	s_nop 0
	global_load_lds_dwordx4 v144, s[30:31]
	s_mov_b32 m0, s38
	s_nop 2
	global_load_lds_dwordx4 v148, s[30:31]
	ds_read_b128 v[184:187], v171 offset:16384
	ds_read_b128 v[188:191], v171 offset:17408
	ds_read_b128 v[192:195], v171 offset:18432
	ds_read_b128 v[196:199], v171 offset:19456
	ds_read_b128 v[200:203], v171 offset:20480
	ds_read_b128 v[204:207], v171 offset:21504
	ds_read_b128 v[208:211], v171 offset:22528
	ds_read_b128 v[212:215], v171 offset:23552
	s_waitcnt vmcnt(8)
	s_waitcnt lgkmcnt(0)
	s_barrier
	s_setprio 1
	s_waitcnt lgkmcnt(0)
	v_mfma_f32_16x16x32_bf16 v[60:63], v[120:123], v[184:187], v[60:63]
	v_mfma_f32_16x16x32_bf16 v[56:59], v[136:139], v[184:187], v[56:59]
	v_mfma_f32_16x16x32_bf16 v[44:47], v[120:123], v[192:195], v[44:47]
	v_mfma_f32_16x16x32_bf16 v[40:43], v[136:139], v[192:195], v[40:43]
	v_mfma_f32_16x16x32_bf16 v[28:31], v[120:123], v[200:203], v[28:31]
	v_mfma_f32_16x16x32_bf16 v[24:27], v[136:139], v[200:203], v[24:27]
	v_mfma_f32_16x16x32_bf16 v[12:15], v[120:123], v[208:211], v[12:15]
	v_mfma_f32_16x16x32_bf16 v[8:11], v[136:139], v[208:211], v[8:11]
	v_mfma_f32_16x16x32_bf16 v[60:63], v[124:127], v[188:191], v[60:63]
	v_mfma_f32_16x16x32_bf16 v[56:59], v[140:143], v[188:191], v[56:59]
	v_mfma_f32_16x16x32_bf16 v[44:47], v[124:127], v[196:199], v[44:47]
	v_mfma_f32_16x16x32_bf16 v[40:43], v[140:143], v[196:199], v[40:43]
	v_mfma_f32_16x16x32_bf16 v[28:31], v[124:127], v[204:207], v[28:31]
	v_mfma_f32_16x16x32_bf16 v[24:27], v[140:143], v[204:207], v[24:27]
	v_mfma_f32_16x16x32_bf16 v[12:15], v[124:127], v[212:215], v[12:15]
	v_mfma_f32_16x16x32_bf16 v[8:11], v[140:143], v[212:215], v[8:11]
	s_nop 0
	s_nop 0
	v_mfma_f32_16x16x32_bf16 v[52:55], v[160:163], v[184:187], v[52:55]
	v_mfma_f32_16x16x32_bf16 v[48:51], v[176:179], v[184:187], v[48:51]
	v_mfma_f32_16x16x32_bf16 v[36:39], v[160:163], v[192:195], v[36:39]
	v_mfma_f32_16x16x32_bf16 v[32:35], v[176:179], v[192:195], v[32:35]
	v_mfma_f32_16x16x32_bf16 v[20:23], v[160:163], v[200:203], v[20:23]
	v_mfma_f32_16x16x32_bf16 v[16:19], v[176:179], v[200:203], v[16:19]
	v_mfma_f32_16x16x32_bf16 v[4:7], v[160:163], v[208:211], v[4:7]
	v_mfma_f32_16x16x32_bf16 v[0:3], v[176:179], v[208:211], v[0:3]
	v_mfma_f32_16x16x32_bf16 v[52:55], v[172:175], v[188:191], v[52:55]
	v_mfma_f32_16x16x32_bf16 v[48:51], v[180:183], v[188:191], v[48:51]
	v_mfma_f32_16x16x32_bf16 v[36:39], v[172:175], v[196:199], v[36:39]
	v_mfma_f32_16x16x32_bf16 v[32:35], v[180:183], v[196:199], v[32:35]
	v_mfma_f32_16x16x32_bf16 v[20:23], v[172:175], v[204:207], v[20:23]
	v_mfma_f32_16x16x32_bf16 v[16:19], v[180:183], v[204:207], v[16:19]
	v_mfma_f32_16x16x32_bf16 v[4:7], v[172:175], v[212:215], v[4:7]
	v_mfma_f32_16x16x32_bf16 v[0:3], v[180:183], v[212:215], v[0:3]
	s_setprio 0
	s_barrier
; #define PG8_STAGE(bufoff, gbase, voff) do { _Pragma("unroll") for (int _i = 0; _i < 2; ++_i) \
;         __builtin_amdgcn_global_load_lds((const unsigned*)((const char*)(gbase) + (voff)[_i]), (LAS unsigned*)(lds + (bufoff) + ldsw + _i * 8192), 16, 0, 0); } while (0)
; #define PG8_LDA(dst, b, h) do { _Pragma("unroll") for (int m = 0; m < 4; ++m) _Pragma("unroll") for (int k = 0; k < 2; ++k) dst[m][k] = *(const LAS bf16x8*)(lds + PG8_SA(b, h) + aoff + m * 2048 + k * 1024); } while (0)
; #define PG8_LDB(dst, b, h) do { _Pragma("unroll") for (int n = 0; n < 2; ++n) _Pragma("unroll") for (int k = 0; k < 2; ++k) dst[n][k] = *(const LAS bf16x8*)(lds + PG8_SB(b, h) + boff + n * 2048 + k * 1024); } while (0)
; #define PG8_MMA(ai, bj, At, Bt) do { __builtin_amdgcn_s_setprio(1); _Pragma("unroll") for (int m = 0; m < 4; ++m) _Pragma("unroll") for (int n = 0; n < 2; ++n) _Pragma("unroll") for (int k = 0; k < 2; ++k) \
;         acc[ai][bj][m][n] = __builtin_amdgcn_mfma_f32_16x16x32_bf16(Bt[n][k], At[m][k], acc[ai][bj][m][n], 0, 0, 0); __builtin_amdgcn_s_setprio(0); } while (0)
; #define PG8_WAIT_V(n) asm volatile("s_waitcnt vmcnt(" #n ")" ::: "memory")
; #define PG8_WAIT_L(n) asm volatile("s_waitcnt lgkmcnt(" #n ")" ::: "memory")
; #define PG8_BAR __builtin_amdgcn_s_barrier()
; #define PG8_SCHED __builtin_amdgcn_sched_barrier(0)
; template <class Epi, class Sched, bool ALIGN_EPI, bool SP2>
; __device__ __forceinline__ void gemm_phase(LAS unsigned char* lds, const Gemm g, const Sched& S, const Epi& E) {
;     ...
;             PG8_LDB(B0, 1, 0); PG8_LDB(B1, 1, 1); PG8_SCHED; PG8_LDA(At, 1, 0); PG8_STAGE(PG8_SA(0, 1), a2 + hstep, voffA);
;             PG8_WAIT_V(8); PG8_WAIT_L(0); PG8_BAR; PG8_MMA(0, 0, At, B0); PG8_MMA(0, 1, At, B1); PG8_BAR; PG8_SCHED;
;             PG8_LDA(At, 1, 1); PG8_STAGE(PG8_SB(1, 0), b3, voffB); PG8_STAGE(PG8_SB(1, 1), b3 + hstep, voffB); PG8_STAGE(PG8_SA(1, 0), a3, voffA);
;             PG8_WAIT_V(8); PG8_WAIT_L(0); PG8_BAR; PG8_MMA(1, 0, At, B0); PG8_MMA(1, 1, At, B1); PG8_BAR; PG8_SCHED;
;     ...
;         }
;         if constexpr (ALIGN_EPI) { if (wr == 0) PG8_BAR; }
	s_add_i32 s57, 0, 0x18000
	s_add_i32 s58, 0, 0x1c000
	v_add_u32_e32 v140, s57, v167
	v_add_u32_e32 v180, s58, v167
	s_add_u32 s24, s30, 0xb0000
	s_addc_u32 s25, s31, 0
	s_mov_b32 m0, s39
	s_nop 0
	global_load_lds_dwordx4 v144, s[24:25]
	s_mov_b32 m0, s40
	s_nop 0
	global_load_lds_dwordx4 v148, s[24:25]
	ds_read_b128 v[120:123], v140
	ds_read_b128 v[124:127], v140 offset:1024
	ds_read_b128 v[136:139], v140 offset:2048
	ds_read_b128 v[140:143], v140 offset:3072
	ds_read_b128 v[160:163], v180
	ds_read_b128 v[172:175], v180 offset:1024
	ds_read_b128 v[176:179], v180 offset:2048
	ds_read_b128 v[180:183], v180 offset:3072
	ds_read_b128 v[184:187], v171 offset:32768
	ds_read_b128 v[188:191], v171 offset:33792
	ds_read_b128 v[192:195], v171 offset:34816
	ds_read_b128 v[196:199], v171 offset:35840
	ds_read_b128 v[200:203], v171 offset:36864
	ds_read_b128 v[204:207], v171 offset:37888
	ds_read_b128 v[208:211], v171 offset:38912
	ds_read_b128 v[212:215], v171 offset:39936
	s_waitcnt vmcnt(8)
	s_waitcnt lgkmcnt(0)
	s_barrier
	s_setprio 1
	s_waitcnt lgkmcnt(0)
	v_mfma_f32_16x16x32_bf16 v[132:135], v[120:123], v[184:187], v[132:135]
	v_mfma_f32_16x16x32_bf16 v[128:131], v[136:139], v[184:187], v[128:131]
	v_mfma_f32_16x16x32_bf16 v[108:111], v[120:123], v[192:195], v[108:111]
	v_mfma_f32_16x16x32_bf16 v[104:107], v[136:139], v[192:195], v[104:107]
	v_mfma_f32_16x16x32_bf16 v[92:95], v[120:123], v[200:203], v[92:95]
	v_mfma_f32_16x16x32_bf16 v[88:91], v[136:139], v[200:203], v[88:91]
	v_mfma_f32_16x16x32_bf16 v[76:79], v[120:123], v[208:211], v[76:79]
	v_mfma_f32_16x16x32_bf16 v[72:75], v[136:139], v[208:211], v[72:75]
	v_mfma_f32_16x16x32_bf16 v[132:135], v[124:127], v[188:191], v[132:135]
	v_mfma_f32_16x16x32_bf16 v[128:131], v[140:143], v[188:191], v[128:131]
	v_mfma_f32_16x16x32_bf16 v[108:111], v[124:127], v[196:199], v[108:111]
	v_mfma_f32_16x16x32_bf16 v[104:107], v[140:143], v[196:199], v[104:107]
	v_mfma_f32_16x16x32_bf16 v[92:95], v[124:127], v[204:207], v[92:95]
	v_mfma_f32_16x16x32_bf16 v[88:91], v[140:143], v[204:207], v[88:91]
	v_mfma_f32_16x16x32_bf16 v[76:79], v[124:127], v[212:215], v[76:79]
	v_mfma_f32_16x16x32_bf16 v[72:75], v[140:143], v[212:215], v[72:75]
	s_nop 0
	s_nop 0
	v_mfma_f32_16x16x32_bf16 v[116:119], v[160:163], v[184:187], v[116:119]
	v_mfma_f32_16x16x32_bf16 v[112:115], v[176:179], v[184:187], v[112:115]
	v_mfma_f32_16x16x32_bf16 v[100:103], v[160:163], v[192:195], v[100:103]
	v_mfma_f32_16x16x32_bf16 v[96:99], v[176:179], v[192:195], v[96:99]
	v_mfma_f32_16x16x32_bf16 v[84:87], v[160:163], v[200:203], v[84:87]
	v_mfma_f32_16x16x32_bf16 v[80:83], v[176:179], v[200:203], v[80:83]
	v_mfma_f32_16x16x32_bf16 v[68:71], v[160:163], v[208:211], v[68:71]
	v_mfma_f32_16x16x32_bf16 v[64:67], v[176:179], v[208:211], v[64:67]
	v_mfma_f32_16x16x32_bf16 v[116:119], v[172:175], v[188:191], v[116:119]
	v_mfma_f32_16x16x32_bf16 v[112:115], v[180:183], v[188:191], v[112:115]
	v_mfma_f32_16x16x32_bf16 v[100:103], v[172:175], v[196:199], v[100:103]
	v_mfma_f32_16x16x32_bf16 v[96:99], v[180:183], v[196:199], v[96:99]
	v_mfma_f32_16x16x32_bf16 v[84:87], v[172:175], v[204:207], v[84:87]
	v_mfma_f32_16x16x32_bf16 v[80:83], v[180:183], v[204:207], v[80:83]
	v_mfma_f32_16x16x32_bf16 v[68:71], v[172:175], v[212:215], v[68:71]
	v_mfma_f32_16x16x32_bf16 v[64:67], v[180:183], v[212:215], v[64:67]
	s_setprio 0
	s_barrier
	s_add_u32 s100, s24, 0xfff50080
	s_addc_u32 s101, s25, -1
	s_add_u32 s98, s28, 0x80
	s_addc_u32 s99, s29, 0
	s_add_i32 s24, s57, s36
	s_mov_b32 m0, s24
	s_nop 0
	global_load_lds_dwordx4 v146, s[98:99]
	s_add_i32 m0, s24, 0x2000
	s_add_u32 s24, s28, 0xb0080
	s_addc_u32 s25, s29, 0
	s_add_i32 s28, s58, s36
	global_load_lds_dwordx4 v150, s[98:99]
	s_mov_b32 m0, s28
	s_nop 0
	global_load_lds_dwordx4 v146, s[24:25]
	s_add_i32 m0, s28, 0x2000
	s_nop 0
	global_load_lds_dwordx4 v150, s[24:25]
	s_mov_b32 m0, s45
	s_nop 0
	global_load_lds_dwordx4 v144, s[100:101]
	s_mov_b32 m0, s46
	s_nop 0
	global_load_lds_dwordx4 v148, s[100:101]
	ds_read_b128 v[184:187], v171 offset:49152
	ds_read_b128 v[188:191], v171 offset:50176
	ds_read_b128 v[192:195], v171 offset:51200
	ds_read_b128 v[196:199], v171 offset:52224
	ds_read_b128 v[200:203], v171 offset:53248
	ds_read_b128 v[204:207], v171 offset:54272
	ds_read_b128 v[208:211], v171 offset:55296
	ds_read_b128 v[212:215], v171 offset:56320
	s_waitcnt vmcnt(8)
	s_waitcnt lgkmcnt(0)
	s_barrier
	s_setprio 1
	s_waitcnt lgkmcnt(0)
	v_mfma_f32_16x16x32_bf16 v[60:63], v[120:123], v[184:187], v[60:63]
	v_mfma_f32_16x16x32_bf16 v[56:59], v[136:139], v[184:187], v[56:59]
	v_mfma_f32_16x16x32_bf16 v[44:47], v[120:123], v[192:195], v[44:47]
	v_mfma_f32_16x16x32_bf16 v[40:43], v[136:139], v[192:195], v[40:43]
	v_mfma_f32_16x16x32_bf16 v[28:31], v[120:123], v[200:203], v[28:31]
	v_mfma_f32_16x16x32_bf16 v[24:27], v[136:139], v[200:203], v[24:27]
	v_mfma_f32_16x16x32_bf16 v[12:15], v[120:123], v[208:211], v[12:15]
	v_mfma_f32_16x16x32_bf16 v[8:11], v[136:139], v[208:211], v[8:11]
	v_mfma_f32_16x16x32_bf16 v[60:63], v[124:127], v[188:191], v[60:63]
	v_mfma_f32_16x16x32_bf16 v[56:59], v[140:143], v[188:191], v[56:59]
	v_mfma_f32_16x16x32_bf16 v[44:47], v[124:127], v[196:199], v[44:47]
	v_mfma_f32_16x16x32_bf16 v[40:43], v[140:143], v[196:199], v[40:43]
	v_mfma_f32_16x16x32_bf16 v[28:31], v[124:127], v[204:207], v[28:31]
	v_mfma_f32_16x16x32_bf16 v[24:27], v[140:143], v[204:207], v[24:27]
	v_mfma_f32_16x16x32_bf16 v[12:15], v[124:127], v[212:215], v[12:15]
	v_mfma_f32_16x16x32_bf16 v[8:11], v[140:143], v[212:215], v[8:11]
	s_nop 0
	s_nop 0
	v_mfma_f32_16x16x32_bf16 v[52:55], v[160:163], v[184:187], v[52:55]
	v_mfma_f32_16x16x32_bf16 v[48:51], v[176:179], v[184:187], v[48:51]
	v_mfma_f32_16x16x32_bf16 v[36:39], v[160:163], v[192:195], v[36:39]
	v_mfma_f32_16x16x32_bf16 v[32:35], v[176:179], v[192:195], v[32:35]
	v_mfma_f32_16x16x32_bf16 v[20:23], v[160:163], v[200:203], v[20:23]
	v_mfma_f32_16x16x32_bf16 v[16:19], v[176:179], v[200:203], v[16:19]
	v_mfma_f32_16x16x32_bf16 v[4:7], v[160:163], v[208:211], v[4:7]
	v_mfma_f32_16x16x32_bf16 v[0:3], v[176:179], v[208:211], v[0:3]
	v_mfma_f32_16x16x32_bf16 v[52:55], v[172:175], v[188:191], v[52:55]
	v_mfma_f32_16x16x32_bf16 v[48:51], v[180:183], v[188:191], v[48:51]
	v_mfma_f32_16x16x32_bf16 v[36:39], v[172:175], v[196:199], v[36:39]
	v_mfma_f32_16x16x32_bf16 v[32:35], v[180:183], v[196:199], v[32:35]
	v_mfma_f32_16x16x32_bf16 v[20:23], v[172:175], v[204:207], v[20:23]
	v_mfma_f32_16x16x32_bf16 v[16:19], v[180:183], v[204:207], v[16:19]
	v_mfma_f32_16x16x32_bf16 v[4:7], v[172:175], v[212:215], v[4:7]
	v_mfma_f32_16x16x32_bf16 v[0:3], v[180:183], v[212:215], v[0:3]
	s_setprio 0
	s_barrier
	s_add_i32 s56, s56, 2
	s_add_u32 s54, s54, 0x100
	s_addc_u32 s55, s55, 0
	s_cmp_gt_u32 s56, 41
	s_mov_b64 s[24:25], s[26:27]
	s_cbranch_scc0 .LBB0_766
	s_and_b64 vcc, exec, s[12:13]
	s_cbranch_vccz .LBB0_769
	s_barrier
